# MFMA-wave priority kept but set outside the MFMA segment: s_setprio 1 in front of the barrier that opens it, s_setprio 0 behind the barrier that closes it (no issue slot between MFMAs)
# speedup vs baseline: 1.0088x; 1.0088x over previous
; #define PG8_STAGE(bufoff, gbase, voff) do { _Pragma("unroll") for (int _i = 0; _i < 2; ++_i) \
;         __builtin_amdgcn_global_load_lds((const unsigned*)((const char*)(gbase) + (voff)[_i]), (LAS unsigned*)(lds + (bufoff) + ldsw + _i * 8192), 16, 0, 0); } while (0)
; #define PG8_LDA(dst, b, h) do { _Pragma("unroll") for (int m = 0; m < 4; ++m) _Pragma("unroll") for (int k = 0; k < 2; ++k) dst[m][k] = *(const LAS bf16x8*)(lds + PG8_SA(b, h) + aoff + m * 2048 + k * 1024); } while (0)
; #define PG8_LDB(dst, b, h) do { _Pragma("unroll") for (int n = 0; n < 2; ++n) _Pragma("unroll") for (int k = 0; k < 2; ++k) dst[n][k] = *(const LAS bf16x8*)(lds + PG8_SB(b, h) + boff + n * 2048 + k * 1024); } while (0)
; #define PG8_WAIT_V(n) asm volatile("s_waitcnt vmcnt(" #n ")" ::: "memory")
; #define PG8_WAIT_L(n) asm volatile("s_waitcnt lgkmcnt(" #n ")" ::: "memory")
; #define PG8_BAR __builtin_amdgcn_s_barrier()
; #define PG8_SCHED __builtin_amdgcn_sched_barrier(0)
; template <class Epi, class Geom, class Sched, bool ALIGN_EPI, bool I8 = false>
; __device__ __forceinline__ void gemm_phase(LAS unsigned char* lds, const Gemm g, const Sched& S, const Epi& E) {
;     ...
;         for (int t = 0; t < nt; t += 2) {
;             const bool last = (t == nt - 2);
;             const char* a1 = cA + (size_t)(t + 1) * kstep;
;             const char* a2 = last ? nA : cA + (size_t)(t + 2) * kstep; const char* b2 = last ? nB : cB + (size_t)(t + 2) * kstep;
;             const char* a3 = a2 + kstep; const char* b3 = b2 + kstep;
;             PG8_LDB(B0, 0, 0); PG8_LDB(B1, 0, 1); PG8_SCHED; PG8_LDA(At, 0, 0); PG8_STAGE(PG8_SA(1, 1), a1 + hsA, voffA);
;             PG8_WAIT_V(8); PG8_WAIT_L(0); PG8_BAR; PG8_MMA(0, 0, At, B0); PG8_MMA(0, 1, At, B1); PG8_BAR; PG8_SCHED;
;             PG8_LDA(At, 0, 1); PG8_STAGE(PG8_SB(0, 0), b2, voffB); PG8_STAGE(PG8_SB(0, 1), b2 + hsB, voffB); PG8_STAGE(PG8_SA(0, 0), a2, voffA);
;             PG8_WAIT_V(8); PG8_WAIT_L(0); PG8_BAR; PG8_MMA(1, 0, At, B0); PG8_MMA(1, 1, At, B1); PG8_BAR; PG8_SCHED;
.LBB0_194:
	ds_read_b128 v[106:109], v241
	ds_read_b128 v[110:113], v241 offset:1024
	ds_read_b128 v[138:141], v241 offset:2048
	ds_read_b128 v[142:145], v241 offset:3072
	ds_read_b128 v[146:149], v242
	ds_read_b128 v[150:153], v242 offset:1024
	ds_read_b128 v[154:157], v242 offset:2048
	ds_read_b128 v[158:161], v242 offset:3072
	s_add_u32 s4, s0, 0xfff00080
	s_addc_u32 s5, s1, -1
	s_cmp_eq_u32 s13, 60
	s_cselect_b32 s7, s3, s5
	s_cselect_b32 s6, s8, s4
	s_cselect_b32 s5, s9, s12
	s_cselect_b32 s4, s10, s11
	v_lshl_add_u64 v[208:209], s[0:1], 0, v[184:185]
	s_add_i32 m0, s73, 0xc000
	ds_read_b128 v[162:165], v243
	ds_read_b128 v[166:169], v243 offset:1024
	ds_read_b128 v[170:173], v243 offset:2048
	ds_read_b128 v[188:191], v243 offset:3072
	ds_read_b128 v[192:195], v243 offset:4096
	ds_read_b128 v[196:199], v243 offset:5120
	ds_read_b128 v[200:203], v243 offset:6144
	ds_read_b128 v[204:207], v243 offset:7168
	global_load_lds_dwordx4 v[208:209], off
	v_lshl_add_u64 v[208:209], s[0:1], 0, v[186:187]
	s_add_i32 m0, s73, 0xe000
	s_nop 0
	global_load_lds_dwordx4 v[208:209], off
	s_waitcnt vmcnt(8)
	s_waitcnt lgkmcnt(0)
	s_setprio 1
	s_barrier
	s_waitcnt lgkmcnt(0)
	v_mfma_f32_16x16x32_bf16 v[122:125], v[106:109], v[162:165], v[122:125]
	v_mfma_f32_16x16x32_bf16 v[126:129], v[138:141], v[162:165], v[126:129]
	v_mfma_f32_16x16x32_bf16 v[102:105], v[106:109], v[170:173], v[102:105]
	v_mfma_f32_16x16x32_bf16 v[98:101], v[138:141], v[170:173], v[98:101]
	v_mfma_f32_16x16x32_bf16 v[94:97], v[106:109], v[192:195], v[94:97]
	v_mfma_f32_16x16x32_bf16 v[86:89], v[138:141], v[192:195], v[86:89]
	v_mfma_f32_16x16x32_bf16 v[78:81], v[106:109], v[200:203], v[78:81]
	v_mfma_f32_16x16x32_bf16 v[70:73], v[138:141], v[200:203], v[70:73]
	v_mfma_f32_16x16x32_bf16 v[122:125], v[110:113], v[166:169], v[122:125]
	v_mfma_f32_16x16x32_bf16 v[126:129], v[142:145], v[166:169], v[126:129]
	v_mfma_f32_16x16x32_bf16 v[102:105], v[110:113], v[188:191], v[102:105]
	v_mfma_f32_16x16x32_bf16 v[98:101], v[142:145], v[188:191], v[98:101]
	v_mfma_f32_16x16x32_bf16 v[94:97], v[110:113], v[196:199], v[94:97]
	v_mfma_f32_16x16x32_bf16 v[86:89], v[142:145], v[196:199], v[86:89]
	v_mfma_f32_16x16x32_bf16 v[78:81], v[110:113], v[204:207], v[78:81]
	v_mfma_f32_16x16x32_bf16 v[70:73], v[142:145], v[204:207], v[70:73]
	v_mfma_f32_16x16x32_bf16 v[118:121], v[146:149], v[162:165], v[118:121]
	v_mfma_f32_16x16x32_bf16 v[114:117], v[154:157], v[162:165], v[114:117]
	v_mfma_f32_16x16x32_bf16 v[90:93], v[146:149], v[170:173], v[90:93]
	v_mfma_f32_16x16x32_bf16 v[82:85], v[154:157], v[170:173], v[82:85]
	v_mfma_f32_16x16x32_bf16 v[74:77], v[146:149], v[192:195], v[74:77]
	v_mfma_f32_16x16x32_bf16 v[66:69], v[154:157], v[192:195], v[66:69]
	v_mfma_f32_16x16x32_bf16 v[62:65], v[146:149], v[200:203], v[62:65]
	v_mfma_f32_16x16x32_bf16 v[58:61], v[154:157], v[200:203], v[58:61]
	v_mfma_f32_16x16x32_bf16 v[118:121], v[150:153], v[166:169], v[118:121]
	v_mfma_f32_16x16x32_bf16 v[114:117], v[158:161], v[166:169], v[114:117]
	v_mfma_f32_16x16x32_bf16 v[90:93], v[150:153], v[188:191], v[90:93]
	v_mfma_f32_16x16x32_bf16 v[82:85], v[158:161], v[188:191], v[82:85]
	v_mfma_f32_16x16x32_bf16 v[74:77], v[150:153], v[196:199], v[74:77]
	v_mfma_f32_16x16x32_bf16 v[66:69], v[158:161], v[196:199], v[66:69]
	v_mfma_f32_16x16x32_bf16 v[62:65], v[150:153], v[204:207], v[62:65]
	v_mfma_f32_16x16x32_bf16 v[58:61], v[158:161], v[204:207], v[58:61]
	s_barrier
	s_setprio 0
	s_add_i32 s14, s34, s89
	v_lshl_add_u64 v[208:209], s[4:5], 0, v[176:177]
	s_mov_b32 m0, s14
	ds_read_b128 v[162:165], v243 offset:16384
	ds_read_b128 v[166:169], v243 offset:17408
	ds_read_b128 v[170:173], v243 offset:18432
	ds_read_b128 v[188:191], v243 offset:19456
	ds_read_b128 v[192:195], v243 offset:20480
	ds_read_b128 v[196:199], v243 offset:21504
	ds_read_b128 v[200:203], v243 offset:22528
	ds_read_b128 v[204:207], v243 offset:23552
	global_load_lds_dwordx4 v[208:209], off
	s_add_i32 m0, s14, 0x2000
	s_add_u32 s14, s4, 0x100000
	v_lshl_add_u64 v[210:211], s[4:5], 0, v[180:181]
	s_addc_u32 s15, s5, 0
	s_add_i32 s16, s35, s89
	global_load_lds_dwordx4 v[210:211], off
	v_lshl_add_u64 v[212:213], s[14:15], 0, v[176:177]
	s_mov_b32 m0, s16
	v_lshl_add_u64 v[214:215], s[6:7], 0, v[178:179]
	global_load_lds_dwordx4 v[212:213], off
	v_lshl_add_u64 v[212:213], s[14:15], 0, v[180:181]
	s_add_i32 m0, s16, 0x2000
	s_nop 0
	global_load_lds_dwordx4 v[212:213], off
	v_lshl_add_u64 v[212:213], s[6:7], 0, v[174:175]
	s_mov_b32 m0, s73
	s_nop 0
	global_load_lds_dwordx4 v[212:213], off
	s_mov_b32 m0, s90
	s_nop 0
	global_load_lds_dwordx4 v[214:215], off
	s_waitcnt vmcnt(8)
	s_waitcnt lgkmcnt(0)
	s_setprio 1
	s_barrier
; #define PG8_STAGE(bufoff, gbase, voff) do { _Pragma("unroll") for (int _i = 0; _i < 2; ++_i) \
;         __builtin_amdgcn_global_load_lds((const unsigned*)((const char*)(gbase) + (voff)[_i]), (LAS unsigned*)(lds + (bufoff) + ldsw + _i * 8192), 16, 0, 0); } while (0)
; #define PG8_LDA(dst, b, h) do { _Pragma("unroll") for (int m = 0; m < 4; ++m) _Pragma("unroll") for (int k = 0; k < 2; ++k) dst[m][k] = *(const LAS bf16x8*)(lds + PG8_SA(b, h) + aoff + m * 2048 + k * 1024); } while (0)
; #define PG8_LDB(dst, b, h) do { _Pragma("unroll") for (int n = 0; n < 2; ++n) _Pragma("unroll") for (int k = 0; k < 2; ++k) dst[n][k] = *(const LAS bf16x8*)(lds + PG8_SB(b, h) + boff + n * 2048 + k * 1024); } while (0)
; #define PG8_WAIT_V(n) asm volatile("s_waitcnt vmcnt(" #n ")" ::: "memory")
; #define PG8_WAIT_L(n) asm volatile("s_waitcnt lgkmcnt(" #n ")" ::: "memory")
; #define PG8_BAR __builtin_amdgcn_s_barrier()
; #define PG8_SCHED __builtin_amdgcn_sched_barrier(0)
; template <class Epi, class Geom, class Sched, bool ALIGN_EPI, bool I8 = false>
; __device__ __forceinline__ void gemm_phase(LAS unsigned char* lds, const Gemm g, const Sched& S, const Epi& E) {
;     ...
;             PG8_WAIT_V(8); PG8_WAIT_L(0); PG8_BAR; PG8_MMA(1, 0, At, B0); PG8_MMA(1, 1, At, B1); PG8_BAR; PG8_SCHED;
;             PG8_LDB(B0, 1, 0); PG8_LDB(B1, 1, 1); PG8_SCHED; PG8_LDA(At, 1, 0); PG8_STAGE(PG8_SA(0, 1), a2 + hsA, voffA);
;             PG8_WAIT_V(8); PG8_WAIT_L(0); PG8_BAR; PG8_MMA(0, 0, At, B0); PG8_MMA(0, 1, At, B1); PG8_BAR; PG8_SCHED;
	s_waitcnt lgkmcnt(0)
	v_mfma_f32_16x16x32_bf16 v[54:57], v[106:109], v[162:165], v[54:57]
	v_mfma_f32_16x16x32_bf16 v[50:53], v[138:141], v[162:165], v[50:53]
	v_mfma_f32_16x16x32_bf16 v[46:49], v[106:109], v[170:173], v[46:49]
	v_mfma_f32_16x16x32_bf16 v[38:41], v[138:141], v[170:173], v[38:41]
	v_mfma_f32_16x16x32_bf16 v[30:33], v[106:109], v[192:195], v[30:33]
	v_mfma_f32_16x16x32_bf16 v[18:21], v[138:141], v[192:195], v[18:21]
	v_mfma_f32_16x16x32_bf16 v[106:109], v[106:109], v[200:203], v[134:137]
	v_mfma_f32_16x16x32_bf16 v[54:57], v[110:113], v[166:169], v[54:57]
	v_mfma_f32_16x16x32_bf16 v[50:53], v[142:145], v[166:169], v[50:53]
	v_mfma_f32_16x16x32_bf16 v[46:49], v[110:113], v[188:191], v[46:49]
	v_mfma_f32_16x16x32_bf16 v[38:41], v[142:145], v[188:191], v[38:41]
	v_mfma_f32_16x16x32_bf16 v[30:33], v[110:113], v[196:199], v[30:33]
	v_mfma_f32_16x16x32_bf16 v[18:21], v[142:145], v[196:199], v[18:21]
	v_mfma_f32_16x16x32_bf16 v[106:109], v[110:113], v[204:207], v[106:109]
	v_mfma_f32_16x16x32_bf16 v[110:113], v[138:141], v[200:203], v[130:133]
	v_mfma_f32_16x16x32_bf16 v[110:113], v[142:145], v[204:207], v[110:113]
	v_mfma_f32_16x16x32_bf16 v[42:45], v[146:149], v[162:165], v[42:45]
	v_mfma_f32_16x16x32_bf16 v[34:37], v[154:157], v[162:165], v[34:37]
	v_mfma_f32_16x16x32_bf16 v[26:29], v[146:149], v[170:173], v[26:29]
	v_mfma_f32_16x16x32_bf16 v[22:25], v[154:157], v[170:173], v[22:25]
	v_mfma_f32_16x16x32_bf16 v[14:17], v[146:149], v[192:195], v[14:17]
	v_mfma_f32_16x16x32_bf16 v[10:13], v[154:157], v[192:195], v[10:13]
	v_mfma_f32_16x16x32_bf16 v[6:9], v[146:149], v[200:203], v[6:9]
	v_mfma_f32_16x16x32_bf16 v[2:5], v[154:157], v[200:203], v[2:5]
	v_mfma_f32_16x16x32_bf16 v[42:45], v[150:153], v[166:169], v[42:45]
	v_mfma_f32_16x16x32_bf16 v[34:37], v[158:161], v[166:169], v[34:37]
	v_mfma_f32_16x16x32_bf16 v[26:29], v[150:153], v[188:191], v[26:29]
	v_mfma_f32_16x16x32_bf16 v[22:25], v[158:161], v[188:191], v[22:25]
	v_mfma_f32_16x16x32_bf16 v[14:17], v[150:153], v[196:199], v[14:17]
	v_mfma_f32_16x16x32_bf16 v[10:13], v[158:161], v[196:199], v[10:13]
	v_mfma_f32_16x16x32_bf16 v[6:9], v[150:153], v[204:207], v[6:9]
	v_mfma_f32_16x16x32_bf16 v[2:5], v[158:161], v[204:207], v[2:5]
	s_barrier
	s_setprio 0
	s_add_i32 s14, 0, 0x18000
	s_add_i32 s15, 0, 0x1c000
	v_add_u32_e32 v142, s14, v240
	v_add_u32_e32 v158, s15, v240
	ds_read_b128 v[130:133], v142
	ds_read_b128 v[134:137], v142 offset:1024
	ds_read_b128 v[138:141], v142 offset:2048
	ds_read_b128 v[142:145], v142 offset:3072
	ds_read_b128 v[146:149], v158
	ds_read_b128 v[150:153], v158 offset:1024
	ds_read_b128 v[154:157], v158 offset:2048
	ds_read_b128 v[158:161], v158 offset:3072
	s_add_u32 s6, s6, 0x100000
	s_addc_u32 s7, s7, 0
	s_mov_b32 m0, s91
	v_lshl_add_u64 v[216:217], s[6:7], 0, v[174:175]
	ds_read_b128 v[162:165], v243 offset:32768
	ds_read_b128 v[166:169], v243 offset:33792
	ds_read_b128 v[170:173], v243 offset:34816
	ds_read_b128 v[188:191], v243 offset:35840
	ds_read_b128 v[192:195], v243 offset:36864
	ds_read_b128 v[196:199], v243 offset:37888
	ds_read_b128 v[200:203], v243 offset:38912
	ds_read_b128 v[204:207], v243 offset:39936
	global_load_lds_dwordx4 v[216:217], off
	v_lshl_add_u64 v[216:217], s[6:7], 0, v[178:179]
	s_mov_b32 m0, s92
	s_nop 0
	global_load_lds_dwordx4 v[216:217], off
	s_waitcnt vmcnt(8)
	s_waitcnt lgkmcnt(0)
	s_setprio 1
	s_barrier
	s_waitcnt lgkmcnt(0)
	v_mfma_f32_16x16x32_bf16 v[122:125], v[130:133], v[162:165], v[122:125]
	v_mfma_f32_16x16x32_bf16 v[126:129], v[138:141], v[162:165], v[126:129]
	v_mfma_f32_16x16x32_bf16 v[102:105], v[130:133], v[170:173], v[102:105]
	v_mfma_f32_16x16x32_bf16 v[98:101], v[138:141], v[170:173], v[98:101]
	v_mfma_f32_16x16x32_bf16 v[94:97], v[130:133], v[192:195], v[94:97]
	v_mfma_f32_16x16x32_bf16 v[86:89], v[138:141], v[192:195], v[86:89]
	v_mfma_f32_16x16x32_bf16 v[78:81], v[130:133], v[200:203], v[78:81]
	v_mfma_f32_16x16x32_bf16 v[70:73], v[138:141], v[200:203], v[70:73]
	v_mfma_f32_16x16x32_bf16 v[122:125], v[134:137], v[166:169], v[122:125]
	v_mfma_f32_16x16x32_bf16 v[126:129], v[142:145], v[166:169], v[126:129]
	v_mfma_f32_16x16x32_bf16 v[102:105], v[134:137], v[188:191], v[102:105]
	v_mfma_f32_16x16x32_bf16 v[98:101], v[142:145], v[188:191], v[98:101]
	v_mfma_f32_16x16x32_bf16 v[94:97], v[134:137], v[196:199], v[94:97]
	v_mfma_f32_16x16x32_bf16 v[86:89], v[142:145], v[196:199], v[86:89]
	v_mfma_f32_16x16x32_bf16 v[78:81], v[134:137], v[204:207], v[78:81]
	v_mfma_f32_16x16x32_bf16 v[70:73], v[142:145], v[204:207], v[70:73]
	v_mfma_f32_16x16x32_bf16 v[118:121], v[146:149], v[162:165], v[118:121]
	v_mfma_f32_16x16x32_bf16 v[114:117], v[154:157], v[162:165], v[114:117]
	v_mfma_f32_16x16x32_bf16 v[90:93], v[146:149], v[170:173], v[90:93]
	v_mfma_f32_16x16x32_bf16 v[82:85], v[154:157], v[170:173], v[82:85]
	v_mfma_f32_16x16x32_bf16 v[74:77], v[146:149], v[192:195], v[74:77]
	v_mfma_f32_16x16x32_bf16 v[66:69], v[154:157], v[192:195], v[66:69]
	v_mfma_f32_16x16x32_bf16 v[62:65], v[146:149], v[200:203], v[62:65]
	v_mfma_f32_16x16x32_bf16 v[58:61], v[154:157], v[200:203], v[58:61]
	v_mfma_f32_16x16x32_bf16 v[118:121], v[150:153], v[166:169], v[118:121]
	v_mfma_f32_16x16x32_bf16 v[114:117], v[158:161], v[166:169], v[114:117]
	v_mfma_f32_16x16x32_bf16 v[90:93], v[150:153], v[188:191], v[90:93]
	v_mfma_f32_16x16x32_bf16 v[82:85], v[158:161], v[188:191], v[82:85]
	v_mfma_f32_16x16x32_bf16 v[74:77], v[150:153], v[196:199], v[74:77]
	v_mfma_f32_16x16x32_bf16 v[66:69], v[158:161], v[196:199], v[66:69]
	v_mfma_f32_16x16x32_bf16 v[62:65], v[150:153], v[204:207], v[62:65]
	v_mfma_f32_16x16x32_bf16 v[58:61], v[158:161], v[204:207], v[58:61]
	s_barrier
; #define PG8_STAGE(bufoff, gbase, voff) do { _Pragma("unroll") for (int _i = 0; _i < 2; ++_i) \
;         __builtin_amdgcn_global_load_lds((const unsigned*)((const char*)(gbase) + (voff)[_i]), (LAS unsigned*)(lds + (bufoff) + ldsw + _i * 8192), 16, 0, 0); } while (0)
; #define PG8_LDA(dst, b, h) do { _Pragma("unroll") for (int m = 0; m < 4; ++m) _Pragma("unroll") for (int k = 0; k < 2; ++k) dst[m][k] = *(const LAS bf16x8*)(lds + PG8_SA(b, h) + aoff + m * 2048 + k * 1024); } while (0)
; #define PG8_WAIT_V(n) asm volatile("s_waitcnt vmcnt(" #n ")" ::: "memory")
; #define PG8_WAIT_L(n) asm volatile("s_waitcnt lgkmcnt(" #n ")" ::: "memory")
; #define PG8_BAR __builtin_amdgcn_s_barrier()
; #define PG8_SCHED __builtin_amdgcn_sched_barrier(0)
; template <class Epi, class Geom, class Sched, bool ALIGN_EPI, bool I8 = false>
; __device__ __forceinline__ void gemm_phase(LAS unsigned char* lds, const Gemm g, const Sched& S, const Epi& E) {
;     ...
;             PG8_LDA(At, 1, 1); PG8_STAGE(PG8_SB(1, 0), b3, voffB); PG8_STAGE(PG8_SB(1, 1), b3 + hsB, voffB); PG8_STAGE(PG8_SA(1, 0), a3, voffA);
;             PG8_WAIT_V(8); PG8_WAIT_L(0); PG8_BAR; PG8_MMA(1, 0, At, B0); PG8_MMA(1, 1, At, B1); PG8_BAR; PG8_SCHED;
;         }
;         if constexpr (ALIGN_EPI) { if (wr == 0) PG8_BAR; }
	s_setprio 0
	s_add_i32 s6, s14, s89
	v_lshl_add_u64 v[208:209], v[208:209], 0, s[28:29]
	s_mov_b32 m0, s6
	ds_read_b128 v[162:165], v243 offset:49152
	ds_read_b128 v[166:169], v243 offset:50176
	ds_read_b128 v[170:173], v243 offset:51200
	ds_read_b128 v[188:191], v243 offset:52224
	ds_read_b128 v[192:195], v243 offset:53248
	ds_read_b128 v[196:199], v243 offset:54272
	ds_read_b128 v[200:203], v243 offset:55296
	ds_read_b128 v[204:207], v243 offset:56320
	global_load_lds_dwordx4 v[208:209], off
	s_add_i32 m0, s6, 0x2000
	s_add_u32 s4, s4, 0x100080
	v_lshl_add_u64 v[208:209], v[210:211], 0, s[28:29]
	s_addc_u32 s5, s5, 0
	s_add_i32 s6, s15, s89
	global_load_lds_dwordx4 v[208:209], off
	v_lshl_add_u64 v[208:209], s[4:5], 0, v[176:177]
	s_mov_b32 m0, s6
	s_nop 0
	global_load_lds_dwordx4 v[208:209], off
	v_lshl_add_u64 v[208:209], s[4:5], 0, v[180:181]
	s_add_i32 m0, s6, 0x2000
	s_nop 0
	global_load_lds_dwordx4 v[208:209], off
	v_lshl_add_u64 v[208:209], v[212:213], 0, s[28:29]
	s_mov_b32 m0, s96
	s_nop 0
	global_load_lds_dwordx4 v[208:209], off
	v_lshl_add_u64 v[208:209], v[214:215], 0, s[28:29]
	s_mov_b32 m0, s97
	s_nop 0
	global_load_lds_dwordx4 v[208:209], off
	s_waitcnt vmcnt(8)
	s_waitcnt lgkmcnt(0)
	s_setprio 1
	s_barrier
	s_waitcnt lgkmcnt(0)
	v_mfma_f32_16x16x32_bf16 v[54:57], v[130:133], v[162:165], v[54:57]
	v_mfma_f32_16x16x32_bf16 v[46:49], v[130:133], v[170:173], v[46:49]
	v_mfma_f32_16x16x32_bf16 v[30:33], v[130:133], v[192:195], v[30:33]
	v_mfma_f32_16x16x32_bf16 v[106:109], v[130:133], v[200:203], v[106:109]
	v_mfma_f32_16x16x32_bf16 v[54:57], v[134:137], v[166:169], v[54:57]
	v_mfma_f32_16x16x32_bf16 v[50:53], v[138:141], v[162:165], v[50:53]
	v_mfma_f32_16x16x32_bf16 v[46:49], v[134:137], v[188:191], v[46:49]
	v_mfma_f32_16x16x32_bf16 v[38:41], v[138:141], v[170:173], v[38:41]
	v_mfma_f32_16x16x32_bf16 v[30:33], v[134:137], v[196:199], v[30:33]
	v_mfma_f32_16x16x32_bf16 v[18:21], v[138:141], v[192:195], v[18:21]
	v_mfma_f32_16x16x32_bf16 v[134:137], v[134:137], v[204:207], v[106:109]
	v_mfma_f32_16x16x32_bf16 v[106:109], v[138:141], v[200:203], v[110:113]
	v_mfma_f32_16x16x32_bf16 v[50:53], v[142:145], v[166:169], v[50:53]
	v_mfma_f32_16x16x32_bf16 v[38:41], v[142:145], v[188:191], v[38:41]
	v_mfma_f32_16x16x32_bf16 v[18:21], v[142:145], v[196:199], v[18:21]
	v_mfma_f32_16x16x32_bf16 v[130:133], v[142:145], v[204:207], v[106:109]
	v_mfma_f32_16x16x32_bf16 v[42:45], v[146:149], v[162:165], v[42:45]
	v_mfma_f32_16x16x32_bf16 v[34:37], v[154:157], v[162:165], v[34:37]
	v_mfma_f32_16x16x32_bf16 v[26:29], v[146:149], v[170:173], v[26:29]
	v_mfma_f32_16x16x32_bf16 v[22:25], v[154:157], v[170:173], v[22:25]
	v_mfma_f32_16x16x32_bf16 v[14:17], v[146:149], v[192:195], v[14:17]
	v_mfma_f32_16x16x32_bf16 v[10:13], v[154:157], v[192:195], v[10:13]
	v_mfma_f32_16x16x32_bf16 v[6:9], v[146:149], v[200:203], v[6:9]
	v_mfma_f32_16x16x32_bf16 v[2:5], v[154:157], v[200:203], v[2:5]
	v_mfma_f32_16x16x32_bf16 v[42:45], v[150:153], v[166:169], v[42:45]
	v_mfma_f32_16x16x32_bf16 v[34:37], v[158:161], v[166:169], v[34:37]
	v_mfma_f32_16x16x32_bf16 v[26:29], v[150:153], v[188:191], v[26:29]
	v_mfma_f32_16x16x32_bf16 v[22:25], v[158:161], v[188:191], v[22:25]
	v_mfma_f32_16x16x32_bf16 v[14:17], v[150:153], v[196:199], v[14:17]
	v_mfma_f32_16x16x32_bf16 v[10:13], v[158:161], v[196:199], v[10:13]
	v_mfma_f32_16x16x32_bf16 v[6:9], v[150:153], v[204:207], v[6:9]
	v_mfma_f32_16x16x32_bf16 v[2:5], v[158:161], v[204:207], v[2:5]
	s_barrier
	s_setprio 0
	s_add_i32 s13, s13, 2
	s_add_u32 s0, s0, 0x100
	s_addc_u32 s1, s1, 0
	s_add_u32 s11, s11, 0x100
	s_addc_u32 s12, s12, 0
	s_cmp_gt_u32 s13, 61
	s_cbranch_scc0 .LBB0_194
	s_and_b64 vcc, exec, s[84:85]
	s_cbranch_vccz .LBB0_197
	s_barrier

;     static __device__ __forceinline__ size_t a_off(const Gemm& g, const Unit& u) { return (size_t)u.pm * 256 * g.lda * 2; }
;     static __device__ __forceinline__ size_t b_off(const Gemm& g, const Unit& u) { return (size_t)u.pn * 256 * g.ldb * 2; }
;     static __device__ __forceinline__ size_t a_off(const Gemm& g, const Unit& u) { return ((size_t)u.pm * 256 * g.lda + (size_t)(u.pn >> 1) * 256) * 2; }
;     static __device__ __forceinline__ size_t b_off(const Gemm& g, const Unit& u) { return (size_t)u.pn * 256 * g.ldb * 2; }
;     __host__ __device__ bool next(int i, Unit& u) const { const long L = (long)i * G + c; if (L >= limit) return false; tile_of((int)L, u); return true; }
;     __host__ __device__ bool next(int i, Unit& u) const { if (i > 0 || c >= nrem * 8) return false; base.tile_of(first + c % nrem, u); u.tl = c % nrem; u.ks = c / nrem; return true; }
;     static __device__ __forceinline__ size_t a_off(const Gemm& g, const Unit& u) { return ((size_t)u.pm * 256 * g.lda + (size_t)u.ks * g.K) * 2; }
; #define PG8_WAIT_V(n) asm volatile("s_waitcnt vmcnt(" #n ")" ::: "memory")
; template <class Epi, class Geom, class Sched, bool ALIGN_EPI, bool I8 = false>
; __device__ __forceinline__ void gemm_phase(LAS unsigned char* lds, const Gemm g, const Sched& S, const Epi& E) {
;     ...
;         const bool has_next = S.next(ui + 1, nxt);
;         const char* nA = has_next ? (const char*)g.A + Geom::a_off(g, nxt) : cA; const char* nB = has_next ? (const char*)g.Bt + Geom::b_off(g, nxt) : cB;
; #pragma unroll 1
;         for (int t = 0; t < nt; t += 2) {
;             const bool last = (t == nt - 2);
;             const char* a1 = cA + (size_t)(t + 1) * kstep;
;             const char* a2 = last ? nA : cA + (size_t)(t + 2) * kstep; const char* b2 = last ? nB : cB + (size_t)(t + 2) * kstep;
;             const char* a3 = a2 + kstep; const char* b3 = b2 + kstep;
;             PG8_LDB(B0, 0, 0); PG8_LDB(B1, 0, 1); PG8_SCHED; PG8_LDA(At, 0, 0); PG8_STAGE(PG8_SA(1, 1), a1 + hsA, voffA);
;             PG8_WAIT_V(8); PG8_WAIT_L(0); PG8_BAR; PG8_MMA(0, 0, At, B0); PG8_MMA(0, 1, At, B1); PG8_BAR; PG8_SCHED;
;             PG8_LDA(At, 0, 1); PG8_STAGE(PG8_SB(0, 0), b2, voffB); PG8_STAGE(PG8_SB(0, 1), b2 + hsB, voffB); PG8_STAGE(PG8_SA(0, 0), a2, voffA);
;             PG8_WAIT_V(8); PG8_WAIT_L(0); PG8_BAR; PG8_MMA(1, 0, At, B0); PG8_MMA(1, 1, At, B1); PG8_BAR; PG8_SCHED;
.LBB0_1860:
	s_add_u32 s35, s26, s34
	s_addc_u32 s40, s27, 0
	s_add_u32 s38, s35, 0x100
	s_addc_u32 s39, s40, 0
	s_and_b64 s[36:37], s[30:31], exec
	s_cselect_b32 s37, s1, s39
	s_cselect_b32 s36, s21, s38
	s_add_u32 s34, s2, s34
	s_addc_u32 s38, s3, 0
	s_add_u32 s34, s34, 0x100
	s_addc_u32 s38, s38, 0
	s_and_b64 s[30:31], s[30:31], exec
	s_cselect_b32 s39, s19, s38
	s_cselect_b32 s38, s63, s34
	s_add_u32 s42, s35, 0x80080
	ds_read_b128 v[50:53], v203
	ds_read_b128 v[54:57], v203 offset:1024
	ds_read_b128 v[58:61], v203 offset:2048
	ds_read_b128 v[122:125], v203 offset:3072
	ds_read_b128 v[126:129], v204
	ds_read_b128 v[130:133], v204 offset:1024
	ds_read_b128 v[168:171], v204 offset:2048
	ds_read_b128 v[172:175], v204 offset:3072
	s_addc_u32 s43, s40, 0
	s_add_i32 s73, s61, s50
	s_add_i32 m0, s53, 0xc000
	s_add_i32 s74, s53, 0xe000
	s_add_i32 s70, s73, 0x2000
	s_add_u32 s40, s38, 0x10000
	s_addc_u32 s41, s39, 0
	s_add_i32 s72, s62, s50
	s_add_i32 s71, s72, 0x2000
	s_add_i32 s69, 0, 0x18000
	s_add_i32 s68, 0, 0x1c000
	s_add_u32 s34, s36, 0x80000
	s_addc_u32 s35, s37, 0
	s_add_i32 s67, s69, s50
	s_add_i32 s65, s67, 0x2000
	s_add_u32 s30, s38, 0x10080
	s_addc_u32 s31, s39, 0
	s_add_i32 s66, s68, s50
	s_add_i32 s64, s66, 0x2000
	v_lshl_add_u64 v[216:217], s[42:43], 0, v[160:161]
	ds_read_b128 v[176:179], v205
	ds_read_b128 v[180:183], v205 offset:1024
	ds_read_b128 v[184:187], v205 offset:2048
	ds_read_b128 v[188:191], v205 offset:3072
	ds_read_b128 v[192:195], v205 offset:4096
	ds_read_b128 v[196:199], v205 offset:5120
	ds_read_b128 v[208:211], v205 offset:6144
	ds_read_b128 v[212:215], v205 offset:7168
	global_load_lds_dwordx4 v[216:217], off
	v_lshl_add_u64 v[216:217], s[42:43], 0, v[156:157]
	s_mov_b32 m0, s74
	s_nop 0
	global_load_lds_dwordx4 v[216:217], off
	s_waitcnt vmcnt(8)
	s_waitcnt lgkmcnt(0)
	s_setprio 1
	s_barrier
	s_waitcnt lgkmcnt(0)
	v_mfma_f32_16x16x32_bf16 v[150:153], v[50:53], v[176:179], v[150:153]
	v_mfma_f32_16x16x32_bf16 v[74:77], v[58:61], v[176:179], v[74:77]
	v_mfma_f32_16x16x32_bf16 v[142:145], v[50:53], v[184:187], v[142:145]
	v_mfma_f32_16x16x32_bf16 v[66:69], v[58:61], v[184:187], v[66:69]
	v_mfma_f32_16x16x32_bf16 v[134:137], v[50:53], v[192:195], v[134:137]
	v_mfma_f32_16x16x32_bf16 v[46:49], v[58:61], v[192:195], v[46:49]
	v_mfma_f32_16x16x32_bf16 v[114:117], v[50:53], v[208:211], v[114:117]
	v_mfma_f32_16x16x32_bf16 v[38:41], v[58:61], v[208:211], v[38:41]
	v_mfma_f32_16x16x32_bf16 v[150:153], v[54:57], v[180:183], v[150:153]
	v_mfma_f32_16x16x32_bf16 v[74:77], v[122:125], v[180:183], v[74:77]
	v_mfma_f32_16x16x32_bf16 v[142:145], v[54:57], v[188:191], v[142:145]
	v_mfma_f32_16x16x32_bf16 v[66:69], v[122:125], v[188:191], v[66:69]
	v_mfma_f32_16x16x32_bf16 v[134:137], v[54:57], v[196:199], v[134:137]
	v_mfma_f32_16x16x32_bf16 v[46:49], v[122:125], v[196:199], v[46:49]
	v_mfma_f32_16x16x32_bf16 v[114:117], v[54:57], v[212:215], v[114:117]
	v_mfma_f32_16x16x32_bf16 v[38:41], v[122:125], v[212:215], v[38:41]
	v_mfma_f32_16x16x32_bf16 v[146:149], v[126:129], v[176:179], v[146:149]
	v_mfma_f32_16x16x32_bf16 v[70:73], v[168:171], v[176:179], v[70:73]
	v_mfma_f32_16x16x32_bf16 v[138:141], v[126:129], v[184:187], v[138:141]
	v_mfma_f32_16x16x32_bf16 v[62:65], v[168:171], v[184:187], v[62:65]
	v_mfma_f32_16x16x32_bf16 v[118:121], v[126:129], v[192:195], v[118:121]
	v_mfma_f32_16x16x32_bf16 v[42:45], v[168:171], v[192:195], v[42:45]
	v_mfma_f32_16x16x32_bf16 v[110:113], v[126:129], v[208:211], v[110:113]
	v_mfma_f32_16x16x32_bf16 v[34:37], v[168:171], v[208:211], v[34:37]
	v_mfma_f32_16x16x32_bf16 v[146:149], v[130:133], v[180:183], v[146:149]
	v_mfma_f32_16x16x32_bf16 v[70:73], v[172:175], v[180:183], v[70:73]
	v_mfma_f32_16x16x32_bf16 v[138:141], v[130:133], v[188:191], v[138:141]
	v_mfma_f32_16x16x32_bf16 v[62:65], v[172:175], v[188:191], v[62:65]
	v_mfma_f32_16x16x32_bf16 v[118:121], v[130:133], v[196:199], v[118:121]
	v_mfma_f32_16x16x32_bf16 v[42:45], v[172:175], v[196:199], v[42:45]
	v_mfma_f32_16x16x32_bf16 v[110:113], v[130:133], v[212:215], v[110:113]
	v_mfma_f32_16x16x32_bf16 v[34:37], v[172:175], v[212:215], v[34:37]
	s_barrier
	s_setprio 0
	s_mov_b32 m0, s73
	v_lshl_add_u64 v[216:217], s[38:39], 0, v[158:159]
	ds_read_b128 v[176:179], v205 offset:16384
	ds_read_b128 v[180:183], v205 offset:17408
	ds_read_b128 v[184:187], v205 offset:18432
	ds_read_b128 v[188:191], v205 offset:19456
	ds_read_b128 v[192:195], v205 offset:20480
	ds_read_b128 v[196:199], v205 offset:21504
	ds_read_b128 v[208:211], v205 offset:22528
	ds_read_b128 v[212:215], v205 offset:23552
	global_load_lds_dwordx4 v[216:217], off
	v_lshl_add_u64 v[218:219], s[38:39], 0, v[154:155]
	s_mov_b32 m0, s70
	v_lshl_add_u64 v[220:221], s[40:41], 0, v[158:159]
	global_load_lds_dwordx4 v[218:219], off
	s_mov_b32 m0, s72
	v_lshl_add_u64 v[222:223], s[36:37], 0, v[156:157]
	global_load_lds_dwordx4 v[220:221], off
	v_lshl_add_u64 v[220:221], s[40:41], 0, v[154:155]
	s_mov_b32 m0, s71
	s_nop 0
	global_load_lds_dwordx4 v[220:221], off
	v_lshl_add_u64 v[220:221], s[36:37], 0, v[160:161]
	s_mov_b32 m0, s53
	s_nop 0
	global_load_lds_dwordx4 v[220:221], off
	s_mov_b32 m0, s54
	s_nop 0
	global_load_lds_dwordx4 v[222:223], off
	s_waitcnt vmcnt(8)
	s_waitcnt lgkmcnt(0)
	s_setprio 1
	s_barrier
; #define PG8_STAGE(bufoff, gbase, voff) do { _Pragma("unroll") for (int _i = 0; _i < 2; ++_i) \
;         __builtin_amdgcn_global_load_lds((const unsigned*)((const char*)(gbase) + (voff)[_i]), (LAS unsigned*)(lds + (bufoff) + ldsw + _i * 8192), 16, 0, 0); } while (0)
; #define PG8_LDA(dst, b, h) do { _Pragma("unroll") for (int m = 0; m < 4; ++m) _Pragma("unroll") for (int k = 0; k < 2; ++k) dst[m][k] = *(const LAS bf16x8*)(lds + PG8_SA(b, h) + aoff + m * 2048 + k * 1024); } while (0)
; #define PG8_LDB(dst, b, h) do { _Pragma("unroll") for (int n = 0; n < 2; ++n) _Pragma("unroll") for (int k = 0; k < 2; ++k) dst[n][k] = *(const LAS bf16x8*)(lds + PG8_SB(b, h) + boff + n * 2048 + k * 1024); } while (0)
; #define PG8_WAIT_V(n) asm volatile("s_waitcnt vmcnt(" #n ")" ::: "memory")
; #define PG8_WAIT_L(n) asm volatile("s_waitcnt lgkmcnt(" #n ")" ::: "memory")
; #define PG8_BAR __builtin_amdgcn_s_barrier()
; #define PG8_SCHED __builtin_amdgcn_sched_barrier(0)
; template <class Epi, class Geom, class Sched, bool ALIGN_EPI, bool I8 = false>
; __device__ __forceinline__ void gemm_phase(LAS unsigned char* lds, const Gemm g, const Sched& S, const Epi& E) {
;     ...
;             PG8_WAIT_V(8); PG8_WAIT_L(0); PG8_BAR; PG8_MMA(1, 0, At, B0); PG8_MMA(1, 1, At, B1); PG8_BAR; PG8_SCHED;
;             PG8_LDB(B0, 1, 0); PG8_LDB(B1, 1, 1); PG8_SCHED; PG8_LDA(At, 1, 0); PG8_STAGE(PG8_SA(0, 1), a2 + hsA, voffA);
;             PG8_WAIT_V(8); PG8_WAIT_L(0); PG8_BAR; PG8_MMA(0, 0, At, B0); PG8_MMA(0, 1, At, B1); PG8_BAR; PG8_SCHED;
	s_waitcnt lgkmcnt(0)
	v_mfma_f32_16x16x32_bf16 v[106:109], v[50:53], v[176:179], v[106:109]
	v_mfma_f32_16x16x32_bf16 v[30:33], v[58:61], v[176:179], v[30:33]
	v_mfma_f32_16x16x32_bf16 v[98:101], v[50:53], v[184:187], v[98:101]
	v_mfma_f32_16x16x32_bf16 v[22:25], v[58:61], v[184:187], v[22:25]
	v_mfma_f32_16x16x32_bf16 v[90:93], v[50:53], v[192:195], v[90:93]
	v_mfma_f32_16x16x32_bf16 v[14:17], v[58:61], v[192:195], v[14:17]
	v_mfma_f32_16x16x32_bf16 v[6:9], v[58:61], v[208:211], v[6:9]
	v_mfma_f32_16x16x32_bf16 v[106:109], v[54:57], v[180:183], v[106:109]
	v_mfma_f32_16x16x32_bf16 v[30:33], v[122:125], v[180:183], v[30:33]
	v_mfma_f32_16x16x32_bf16 v[98:101], v[54:57], v[188:191], v[98:101]
	v_mfma_f32_16x16x32_bf16 v[22:25], v[122:125], v[188:191], v[22:25]
	v_mfma_f32_16x16x32_bf16 v[90:93], v[54:57], v[196:199], v[90:93]
	v_mfma_f32_16x16x32_bf16 v[14:17], v[122:125], v[196:199], v[14:17]
	v_mfma_f32_16x16x32_bf16 v[50:53], v[50:53], v[208:211], v[82:85]
	v_mfma_f32_16x16x32_bf16 v[6:9], v[122:125], v[212:215], v[6:9]
	v_mfma_f32_16x16x32_bf16 v[50:53], v[54:57], v[212:215], v[50:53]
	v_mfma_f32_16x16x32_bf16 v[26:29], v[168:171], v[176:179], v[26:29]
	v_mfma_f32_16x16x32_bf16 v[18:21], v[168:171], v[184:187], v[18:21]
	v_mfma_f32_16x16x32_bf16 v[82:85], v[126:129], v[192:195], v[86:89]
	v_mfma_f32_16x16x32_bf16 v[10:13], v[168:171], v[192:195], v[10:13]
	v_mfma_f32_16x16x32_bf16 v[78:81], v[126:129], v[208:211], v[78:81]
	v_mfma_f32_16x16x32_bf16 v[2:5], v[168:171], v[208:211], v[2:5]
	v_mfma_f32_16x16x32_bf16 v[54:57], v[126:129], v[176:179], v[102:105]
	v_mfma_f32_16x16x32_bf16 v[26:29], v[172:175], v[180:183], v[26:29]
	v_mfma_f32_16x16x32_bf16 v[58:61], v[126:129], v[184:187], v[94:97]
	v_mfma_f32_16x16x32_bf16 v[18:21], v[172:175], v[188:191], v[18:21]
	v_mfma_f32_16x16x32_bf16 v[86:89], v[130:133], v[196:199], v[82:85]
	v_mfma_f32_16x16x32_bf16 v[10:13], v[172:175], v[196:199], v[10:13]
	v_mfma_f32_16x16x32_bf16 v[78:81], v[130:133], v[212:215], v[78:81]
	v_mfma_f32_16x16x32_bf16 v[2:5], v[172:175], v[212:215], v[2:5]
	v_mfma_f32_16x16x32_bf16 v[54:57], v[130:133], v[180:183], v[54:57]
	v_mfma_f32_16x16x32_bf16 v[58:61], v[130:133], v[188:191], v[58:61]
	s_barrier
	s_setprio 0
	v_add_u32_e32 v122, s69, v200
	v_add_u32_e32 v162, s68, v200
	ds_read_b128 v[82:85], v122
	ds_read_b128 v[94:97], v122 offset:1024
	ds_read_b128 v[102:105], v122 offset:2048
	ds_read_b128 v[122:125], v122 offset:3072
	ds_read_b128 v[126:129], v162
	ds_read_b128 v[130:133], v162 offset:1024
	ds_read_b128 v[168:171], v162 offset:2048
	ds_read_b128 v[172:175], v162 offset:3072
	s_mov_b32 m0, s55
	v_lshl_add_u64 v[224:225], s[34:35], 0, v[160:161]
	ds_read_b128 v[176:179], v205 offset:32768
	ds_read_b128 v[180:183], v205 offset:33792
	ds_read_b128 v[184:187], v205 offset:34816
	ds_read_b128 v[188:191], v205 offset:35840
	ds_read_b128 v[192:195], v205 offset:36864
	ds_read_b128 v[196:199], v205 offset:37888
	ds_read_b128 v[208:211], v205 offset:38912
	ds_read_b128 v[212:215], v205 offset:39936
	global_load_lds_dwordx4 v[224:225], off
	v_lshl_add_u64 v[224:225], s[34:35], 0, v[156:157]
	s_mov_b32 m0, s56
	s_nop 0
	global_load_lds_dwordx4 v[224:225], off
	s_waitcnt vmcnt(8)
	s_waitcnt lgkmcnt(0)
	s_setprio 1
	s_barrier
	s_waitcnt lgkmcnt(0)
	v_mfma_f32_16x16x32_bf16 v[150:153], v[82:85], v[176:179], v[150:153]
	v_mfma_f32_16x16x32_bf16 v[74:77], v[102:105], v[176:179], v[74:77]
	v_mfma_f32_16x16x32_bf16 v[142:145], v[82:85], v[184:187], v[142:145]
	v_mfma_f32_16x16x32_bf16 v[66:69], v[102:105], v[184:187], v[66:69]
	v_mfma_f32_16x16x32_bf16 v[134:137], v[82:85], v[192:195], v[134:137]
	v_mfma_f32_16x16x32_bf16 v[46:49], v[102:105], v[192:195], v[46:49]
	v_mfma_f32_16x16x32_bf16 v[114:117], v[82:85], v[208:211], v[114:117]
	v_mfma_f32_16x16x32_bf16 v[38:41], v[102:105], v[208:211], v[38:41]
	v_mfma_f32_16x16x32_bf16 v[150:153], v[94:97], v[180:183], v[150:153]
	v_mfma_f32_16x16x32_bf16 v[74:77], v[122:125], v[180:183], v[74:77]
	v_mfma_f32_16x16x32_bf16 v[142:145], v[94:97], v[188:191], v[142:145]
	v_mfma_f32_16x16x32_bf16 v[66:69], v[122:125], v[188:191], v[66:69]
	v_mfma_f32_16x16x32_bf16 v[134:137], v[94:97], v[196:199], v[134:137]
	v_mfma_f32_16x16x32_bf16 v[46:49], v[122:125], v[196:199], v[46:49]
	v_mfma_f32_16x16x32_bf16 v[114:117], v[94:97], v[212:215], v[114:117]
	v_mfma_f32_16x16x32_bf16 v[38:41], v[122:125], v[212:215], v[38:41]
	v_mfma_f32_16x16x32_bf16 v[146:149], v[126:129], v[176:179], v[146:149]
	v_mfma_f32_16x16x32_bf16 v[70:73], v[168:171], v[176:179], v[70:73]
	v_mfma_f32_16x16x32_bf16 v[138:141], v[126:129], v[184:187], v[138:141]
	v_mfma_f32_16x16x32_bf16 v[62:65], v[168:171], v[184:187], v[62:65]
	v_mfma_f32_16x16x32_bf16 v[118:121], v[126:129], v[192:195], v[118:121]
	v_mfma_f32_16x16x32_bf16 v[42:45], v[168:171], v[192:195], v[42:45]
	v_mfma_f32_16x16x32_bf16 v[110:113], v[126:129], v[208:211], v[110:113]
	v_mfma_f32_16x16x32_bf16 v[34:37], v[168:171], v[208:211], v[34:37]
	v_mfma_f32_16x16x32_bf16 v[146:149], v[130:133], v[180:183], v[146:149]
	v_mfma_f32_16x16x32_bf16 v[70:73], v[172:175], v[180:183], v[70:73]
	v_mfma_f32_16x16x32_bf16 v[138:141], v[130:133], v[188:191], v[138:141]
	v_mfma_f32_16x16x32_bf16 v[62:65], v[172:175], v[188:191], v[62:65]
	v_mfma_f32_16x16x32_bf16 v[118:121], v[130:133], v[196:199], v[118:121]
	v_mfma_f32_16x16x32_bf16 v[42:45], v[172:175], v[196:199], v[42:45]
	v_mfma_f32_16x16x32_bf16 v[110:113], v[130:133], v[212:215], v[110:113]
	v_mfma_f32_16x16x32_bf16 v[34:37], v[172:175], v[212:215], v[34:37]
	s_barrier
; #define PG8_STAGE(bufoff, gbase, voff) do { _Pragma("unroll") for (int _i = 0; _i < 2; ++_i) \
;         __builtin_amdgcn_global_load_lds((const unsigned*)((const char*)(gbase) + (voff)[_i]), (LAS unsigned*)(lds + (bufoff) + ldsw + _i * 8192), 16, 0, 0); } while (0)
; #define PG8_LDA(dst, b, h) do { _Pragma("unroll") for (int m = 0; m < 4; ++m) _Pragma("unroll") for (int k = 0; k < 2; ++k) dst[m][k] = *(const LAS bf16x8*)(lds + PG8_SA(b, h) + aoff + m * 2048 + k * 1024); } while (0)
; #define PG8_WAIT_V(n) asm volatile("s_waitcnt vmcnt(" #n ")" ::: "memory")
; #define PG8_WAIT_L(n) asm volatile("s_waitcnt lgkmcnt(" #n ")" ::: "memory")
; #define PG8_BAR __builtin_amdgcn_s_barrier()
; #define PG8_SCHED __builtin_amdgcn_sched_barrier(0)
; template <class Epi, class Geom, class Sched, bool ALIGN_EPI, bool I8 = false>
; __device__ __forceinline__ void gemm_phase(LAS unsigned char* lds, const Gemm g, const Sched& S, const Epi& E) {
;     ...
;             PG8_LDA(At, 1, 1); PG8_STAGE(PG8_SB(1, 0), b3, voffB); PG8_STAGE(PG8_SB(1, 1), b3 + hsB, voffB); PG8_STAGE(PG8_SA(1, 0), a3, voffA);
;             PG8_WAIT_V(8); PG8_WAIT_L(0); PG8_BAR; PG8_MMA(1, 0, At, B0); PG8_MMA(1, 1, At, B1); PG8_BAR; PG8_SCHED;
;         }
;         if constexpr (ALIGN_EPI) { if (wr == 0) PG8_BAR; }
;         E(acc, cur, wr, wc, fr, fq);
;         if (!has_next) break;
	s_setprio 0
	s_mov_b32 m0, s67
	v_lshl_add_u64 v[216:217], v[216:217], 0, s[14:15]
	ds_read_b128 v[176:179], v205 offset:49152
	ds_read_b128 v[180:183], v205 offset:50176
	ds_read_b128 v[184:187], v205 offset:51200
	ds_read_b128 v[188:191], v205 offset:52224
	ds_read_b128 v[192:195], v205 offset:53248
	ds_read_b128 v[196:199], v205 offset:54272
	ds_read_b128 v[208:211], v205 offset:55296
	ds_read_b128 v[212:215], v205 offset:56320
	global_load_lds_dwordx4 v[216:217], off
	v_lshl_add_u64 v[216:217], v[218:219], 0, s[14:15]
	s_mov_b32 m0, s65
	s_nop 0
	global_load_lds_dwordx4 v[216:217], off
	v_lshl_add_u64 v[216:217], s[30:31], 0, v[158:159]
	s_mov_b32 m0, s66
	s_nop 0
	global_load_lds_dwordx4 v[216:217], off
	v_lshl_add_u64 v[216:217], s[30:31], 0, v[154:155]
	s_mov_b32 m0, s64
	s_nop 0
	global_load_lds_dwordx4 v[216:217], off
	v_lshl_add_u64 v[216:217], v[220:221], 0, s[14:15]
	s_mov_b32 m0, s58
	s_nop 0
	global_load_lds_dwordx4 v[216:217], off
	v_lshl_add_u64 v[216:217], v[222:223], 0, s[14:15]
	s_mov_b32 m0, s59
	s_nop 0
	global_load_lds_dwordx4 v[216:217], off
	s_waitcnt vmcnt(8)
	s_waitcnt lgkmcnt(0)
	s_setprio 1
	s_barrier
	s_waitcnt lgkmcnt(0)
	v_mfma_f32_16x16x32_bf16 v[106:109], v[82:85], v[176:179], v[106:109]
	v_mfma_f32_16x16x32_bf16 v[30:33], v[102:105], v[176:179], v[30:33]
	v_mfma_f32_16x16x32_bf16 v[98:101], v[82:85], v[184:187], v[98:101]
	v_mfma_f32_16x16x32_bf16 v[22:25], v[102:105], v[184:187], v[22:25]
	v_mfma_f32_16x16x32_bf16 v[90:93], v[82:85], v[192:195], v[90:93]
	v_mfma_f32_16x16x32_bf16 v[14:17], v[102:105], v[192:195], v[14:17]
	v_mfma_f32_16x16x32_bf16 v[50:53], v[82:85], v[208:211], v[50:53]
	v_mfma_f32_16x16x32_bf16 v[6:9], v[102:105], v[208:211], v[6:9]
	v_mfma_f32_16x16x32_bf16 v[106:109], v[94:97], v[180:183], v[106:109]
	v_mfma_f32_16x16x32_bf16 v[30:33], v[122:125], v[180:183], v[30:33]
	v_mfma_f32_16x16x32_bf16 v[98:101], v[94:97], v[188:191], v[98:101]
	v_mfma_f32_16x16x32_bf16 v[22:25], v[122:125], v[188:191], v[22:25]
	v_mfma_f32_16x16x32_bf16 v[90:93], v[94:97], v[196:199], v[90:93]
	v_mfma_f32_16x16x32_bf16 v[14:17], v[122:125], v[196:199], v[14:17]
	v_mfma_f32_16x16x32_bf16 v[82:85], v[94:97], v[212:215], v[50:53]
	v_mfma_f32_16x16x32_bf16 v[6:9], v[122:125], v[212:215], v[6:9]
	v_mfma_f32_16x16x32_bf16 v[50:53], v[126:129], v[176:179], v[54:57]
	v_mfma_f32_16x16x32_bf16 v[102:105], v[130:133], v[180:183], v[50:53]
	v_mfma_f32_16x16x32_bf16 v[50:53], v[126:129], v[184:187], v[58:61]
	v_mfma_f32_16x16x32_bf16 v[94:97], v[130:133], v[188:191], v[50:53]
	v_mfma_f32_16x16x32_bf16 v[50:53], v[126:129], v[192:195], v[86:89]
	v_mfma_f32_16x16x32_bf16 v[26:29], v[168:171], v[176:179], v[26:29]
	v_mfma_f32_16x16x32_bf16 v[18:21], v[168:171], v[184:187], v[18:21]
	v_mfma_f32_16x16x32_bf16 v[86:89], v[130:133], v[196:199], v[50:53]
	v_mfma_f32_16x16x32_bf16 v[10:13], v[168:171], v[192:195], v[10:13]
	v_mfma_f32_16x16x32_bf16 v[50:53], v[126:129], v[208:211], v[78:81]
	v_mfma_f32_16x16x32_bf16 v[2:5], v[168:171], v[208:211], v[2:5]
	v_mfma_f32_16x16x32_bf16 v[26:29], v[172:175], v[180:183], v[26:29]
	v_mfma_f32_16x16x32_bf16 v[18:21], v[172:175], v[188:191], v[18:21]
	v_mfma_f32_16x16x32_bf16 v[10:13], v[172:175], v[196:199], v[10:13]
	v_mfma_f32_16x16x32_bf16 v[78:81], v[130:133], v[212:215], v[50:53]
	v_mfma_f32_16x16x32_bf16 v[2:5], v[172:175], v[212:215], v[2:5]
	s_barrier
	s_setprio 0
	s_movk_i32 s34, 0x100
	s_andn2_b64 vcc, exec, s[28:29]
	s_mov_b64 s[30:31], -1
	s_mov_b64 s[28:29], 0
	s_cbranch_vccz .LBB0_1860
	s_and_b64 vcc, exec, s[16:17]
	s_cbranch_vccz .LBB0_1863
	s_barrier

; #define PG8_STAGE(bufoff, gbase, voff) do { _Pragma("unroll") for (int _i = 0; _i < 2; ++_i) \
;         __builtin_amdgcn_global_load_lds((const unsigned*)((const char*)(gbase) + (voff)[_i]), (LAS unsigned*)(lds + (bufoff) + ldsw + _i * 8192), 16, 0, 0); } while (0)
; #define PG8_LDA(dst, b, h) do { _Pragma("unroll") for (int m = 0; m < 4; ++m) _Pragma("unroll") for (int k = 0; k < 2; ++k) dst[m][k] = *(const LAS bf16x8*)(lds + PG8_SA(b, h) + aoff + m * 2048 + k * 1024); } while (0)
; #define PG8_LDB(dst, b, h) do { _Pragma("unroll") for (int n = 0; n < 2; ++n) _Pragma("unroll") for (int k = 0; k < 2; ++k) dst[n][k] = *(const LAS bf16x8*)(lds + PG8_SB(b, h) + boff + n * 2048 + k * 1024); } while (0)
; #define PG8_WAIT_V(n) asm volatile("s_waitcnt vmcnt(" #n ")" ::: "memory")
; #define PG8_WAIT_L(n) asm volatile("s_waitcnt lgkmcnt(" #n ")" ::: "memory")
; #define PG8_BAR __builtin_amdgcn_s_barrier()
; #define PG8_SCHED __builtin_amdgcn_sched_barrier(0)
; template <class Epi, class Geom, class Sched, bool ALIGN_EPI, bool I8 = false>
; __device__ __forceinline__ void gemm_phase(LAS unsigned char* lds, const Gemm g, const Sched& S, const Epi& E) {
;     ...
;         for (int t = 0; t < nt; t += 2) {
;             const bool last = (t == nt - 2);
;             const char* a1 = cA + (size_t)(t + 1) * kstep;
;             const char* a2 = last ? nA : cA + (size_t)(t + 2) * kstep; const char* b2 = last ? nB : cB + (size_t)(t + 2) * kstep;
;             const char* a3 = a2 + kstep; const char* b3 = b2 + kstep;
;             PG8_LDB(B0, 0, 0); PG8_LDB(B1, 0, 1); PG8_SCHED; PG8_LDA(At, 0, 0); PG8_STAGE(PG8_SA(1, 1), a1 + hsA, voffA);
;             PG8_WAIT_V(8); PG8_WAIT_L(0); PG8_BAR; PG8_MMA(0, 0, At, B0); PG8_MMA(0, 1, At, B1); PG8_BAR; PG8_SCHED;
;             PG8_LDA(At, 0, 1); PG8_STAGE(PG8_SB(0, 0), b2, voffB); PG8_STAGE(PG8_SB(0, 1), b2 + hsB, voffB); PG8_STAGE(PG8_SA(0, 0), a2, voffA);
;             PG8_WAIT_V(8); PG8_WAIT_L(0); PG8_BAR; PG8_MMA(1, 0, At, B0); PG8_MMA(1, 1, At, B1); PG8_BAR; PG8_SCHED;
.LBB0_2231:
	ds_read_b128 v[102:105], v166
	ds_read_b128 v[106:109], v166 offset:1024
	ds_read_b128 v[114:117], v166 offset:2048
	ds_read_b128 v[118:121], v166 offset:3072
	ds_read_b128 v[156:159], v167
	ds_read_b128 v[170:173], v167 offset:1024
	ds_read_b128 v[174:177], v167 offset:2048
	ds_read_b128 v[178:181], v167 offset:3072
	s_add_u32 s34, s30, 0xfff80080
	s_addc_u32 s35, s31, -1
	s_cmp_eq_u32 s61, 28
	s_cselect_b32 s37, s23, s35
	s_cselect_b32 s36, s57, s34
	s_cselect_b32 s35, s21, s60
	s_cselect_b32 s34, s58, s59
	v_lshl_add_u64 v[160:161], s[30:31], 0, v[150:151]
	s_add_i32 m0, s29, 0xc000
	ds_read_b128 v[182:185], v168
	ds_read_b128 v[186:189], v168 offset:1024
	ds_read_b128 v[190:193], v168 offset:2048
	ds_read_b128 v[194:197], v168 offset:3072
	ds_read_b128 v[198:201], v168 offset:4096
	ds_read_b128 v[202:205], v168 offset:5120
	ds_read_b128 v[206:209], v168 offset:6144
	ds_read_b128 v[210:213], v168 offset:7168
	global_load_lds_dwordx4 v[160:161], off
	v_lshl_add_u64 v[160:161], s[30:31], 0, v[152:153]
	s_add_i32 m0, s29, 0xe000
	s_nop 0
	global_load_lds_dwordx4 v[160:161], off
	s_waitcnt vmcnt(8)
	s_waitcnt lgkmcnt(0)
	s_setprio 1
	s_barrier
	s_waitcnt lgkmcnt(0)
	v_mfma_i32_16x16x64_i8 v[142:145], v[102:105], v[182:185], v[142:145]
	v_mfma_i32_16x16x64_i8 v[138:141], v[114:117], v[182:185], v[138:141]
	v_mfma_i32_16x16x64_i8 v[126:129], v[102:105], v[190:193], v[126:129]
	v_mfma_i32_16x16x64_i8 v[122:125], v[114:117], v[190:193], v[122:125]
	v_mfma_i32_16x16x64_i8 v[94:97], v[102:105], v[198:201], v[94:97]
	v_mfma_i32_16x16x64_i8 v[90:93], v[114:117], v[198:201], v[90:93]
	v_mfma_i32_16x16x64_i8 v[82:85], v[102:105], v[206:209], v[82:85]
	v_mfma_i32_16x16x64_i8 v[74:77], v[114:117], v[206:209], v[74:77]
	v_mfma_i32_16x16x64_i8 v[142:145], v[106:109], v[186:189], v[142:145]
	v_mfma_i32_16x16x64_i8 v[138:141], v[118:121], v[186:189], v[138:141]
	v_mfma_i32_16x16x64_i8 v[126:129], v[106:109], v[194:197], v[126:129]
	v_mfma_i32_16x16x64_i8 v[122:125], v[118:121], v[194:197], v[122:125]
	v_mfma_i32_16x16x64_i8 v[94:97], v[106:109], v[202:205], v[94:97]
	v_mfma_i32_16x16x64_i8 v[90:93], v[118:121], v[202:205], v[90:93]
	v_mfma_i32_16x16x64_i8 v[82:85], v[106:109], v[210:213], v[82:85]
	v_mfma_i32_16x16x64_i8 v[74:77], v[118:121], v[210:213], v[74:77]
	v_mfma_i32_16x16x64_i8 v[134:137], v[156:159], v[182:185], v[134:137]
	v_mfma_i32_16x16x64_i8 v[130:133], v[174:177], v[182:185], v[130:133]
	v_mfma_i32_16x16x64_i8 v[110:113], v[156:159], v[190:193], v[110:113]
	v_mfma_i32_16x16x64_i8 v[98:101], v[174:177], v[190:193], v[98:101]
	v_mfma_i32_16x16x64_i8 v[86:89], v[156:159], v[198:201], v[86:89]
	v_mfma_i32_16x16x64_i8 v[78:81], v[174:177], v[198:201], v[78:81]
	v_mfma_i32_16x16x64_i8 v[70:73], v[156:159], v[206:209], v[70:73]
	v_mfma_i32_16x16x64_i8 v[66:69], v[174:177], v[206:209], v[66:69]
	v_mfma_i32_16x16x64_i8 v[134:137], v[170:173], v[186:189], v[134:137]
	v_mfma_i32_16x16x64_i8 v[130:133], v[178:181], v[186:189], v[130:133]
	v_mfma_i32_16x16x64_i8 v[110:113], v[170:173], v[194:197], v[110:113]
	v_mfma_i32_16x16x64_i8 v[98:101], v[178:181], v[194:197], v[98:101]
	v_mfma_i32_16x16x64_i8 v[86:89], v[170:173], v[202:205], v[86:89]
	v_mfma_i32_16x16x64_i8 v[78:81], v[178:181], v[202:205], v[78:81]
	v_mfma_i32_16x16x64_i8 v[70:73], v[170:173], v[210:213], v[70:73]
	v_mfma_i32_16x16x64_i8 v[66:69], v[178:181], v[210:213], v[66:69]
	s_barrier
	s_setprio 0
	s_add_i32 s62, s10, s41
	v_lshl_add_u64 v[160:161], s[34:35], 0, v[146:147]
	s_mov_b32 m0, s62
	ds_read_b128 v[182:185], v168 offset:16384
	ds_read_b128 v[186:189], v168 offset:17408
	ds_read_b128 v[190:193], v168 offset:18432
	ds_read_b128 v[194:197], v168 offset:19456
	ds_read_b128 v[198:201], v168 offset:20480
	ds_read_b128 v[202:205], v168 offset:21504
	ds_read_b128 v[206:209], v168 offset:22528
	ds_read_b128 v[210:213], v168 offset:23552
	global_load_lds_dwordx4 v[160:161], off
	s_add_i32 m0, s62, 0x2000
	s_add_u32 s62, s34, 0x80000
	v_lshl_add_u64 v[214:215], s[34:35], 0, v[148:149]
	s_addc_u32 s63, s35, 0
	s_add_i32 s64, s50, s41
	global_load_lds_dwordx4 v[214:215], off
	v_lshl_add_u64 v[216:217], s[62:63], 0, v[146:147]
	s_mov_b32 m0, s64
	v_lshl_add_u64 v[218:219], s[36:37], 0, v[148:149]
	global_load_lds_dwordx4 v[216:217], off
	v_lshl_add_u64 v[216:217], s[62:63], 0, v[148:149]
	s_add_i32 m0, s64, 0x2000
	s_nop 0
	global_load_lds_dwordx4 v[216:217], off
	v_lshl_add_u64 v[216:217], s[36:37], 0, v[146:147]
	s_mov_b32 m0, s29
	s_nop 0
	global_load_lds_dwordx4 v[216:217], off
	s_mov_b32 m0, s44
	s_nop 0
	global_load_lds_dwordx4 v[218:219], off
	s_waitcnt vmcnt(8)
	s_waitcnt lgkmcnt(0)
	s_setprio 1
	s_barrier
; #define PG8_STAGE(bufoff, gbase, voff) do { _Pragma("unroll") for (int _i = 0; _i < 2; ++_i) \
;         __builtin_amdgcn_global_load_lds((const unsigned*)((const char*)(gbase) + (voff)[_i]), (LAS unsigned*)(lds + (bufoff) + ldsw + _i * 8192), 16, 0, 0); } while (0)
; #define PG8_LDA(dst, b, h) do { _Pragma("unroll") for (int m = 0; m < 4; ++m) _Pragma("unroll") for (int k = 0; k < 2; ++k) dst[m][k] = *(const LAS bf16x8*)(lds + PG8_SA(b, h) + aoff + m * 2048 + k * 1024); } while (0)
; #define PG8_LDB(dst, b, h) do { _Pragma("unroll") for (int n = 0; n < 2; ++n) _Pragma("unroll") for (int k = 0; k < 2; ++k) dst[n][k] = *(const LAS bf16x8*)(lds + PG8_SB(b, h) + boff + n * 2048 + k * 1024); } while (0)
; #define PG8_WAIT_V(n) asm volatile("s_waitcnt vmcnt(" #n ")" ::: "memory")
; #define PG8_WAIT_L(n) asm volatile("s_waitcnt lgkmcnt(" #n ")" ::: "memory")
; #define PG8_BAR __builtin_amdgcn_s_barrier()
; #define PG8_SCHED __builtin_amdgcn_sched_barrier(0)
; template <class Epi, class Geom, class Sched, bool ALIGN_EPI, bool I8 = false>
; __device__ __forceinline__ void gemm_phase(LAS unsigned char* lds, const Gemm g, const Sched& S, const Epi& E) {
;     ...
;             PG8_WAIT_V(8); PG8_WAIT_L(0); PG8_BAR; PG8_MMA(1, 0, At, B0); PG8_MMA(1, 1, At, B1); PG8_BAR; PG8_SCHED;
;             PG8_LDB(B0, 1, 0); PG8_LDB(B1, 1, 1); PG8_SCHED; PG8_LDA(At, 1, 0); PG8_STAGE(PG8_SA(0, 1), a2 + hsA, voffA);
;             PG8_WAIT_V(8); PG8_WAIT_L(0); PG8_BAR; PG8_MMA(0, 0, At, B0); PG8_MMA(0, 1, At, B1); PG8_BAR; PG8_SCHED;
	s_waitcnt lgkmcnt(0)
	v_mfma_i32_16x16x64_i8 v[62:65], v[102:105], v[182:185], v[62:65]
	v_mfma_i32_16x16x64_i8 v[58:61], v[114:117], v[182:185], v[58:61]
	v_mfma_i32_16x16x64_i8 v[50:53], v[102:105], v[190:193], v[50:53]
	v_mfma_i32_16x16x64_i8 v[42:45], v[114:117], v[190:193], v[42:45]
	v_mfma_i32_16x16x64_i8 v[30:33], v[102:105], v[198:201], v[30:33]
	v_mfma_i32_16x16x64_i8 v[26:29], v[114:117], v[198:201], v[26:29]
	v_mfma_i32_16x16x64_i8 v[18:21], v[102:105], v[206:209], v[18:21]
	v_mfma_i32_16x16x64_i8 v[10:13], v[114:117], v[206:209], v[10:13]
	v_mfma_i32_16x16x64_i8 v[62:65], v[106:109], v[186:189], v[62:65]
	v_mfma_i32_16x16x64_i8 v[58:61], v[118:121], v[186:189], v[58:61]
	v_mfma_i32_16x16x64_i8 v[50:53], v[106:109], v[194:197], v[50:53]
	v_mfma_i32_16x16x64_i8 v[42:45], v[118:121], v[194:197], v[42:45]
	v_mfma_i32_16x16x64_i8 v[30:33], v[106:109], v[202:205], v[30:33]
	v_mfma_i32_16x16x64_i8 v[26:29], v[118:121], v[202:205], v[26:29]
	v_mfma_i32_16x16x64_i8 v[18:21], v[106:109], v[210:213], v[18:21]
	v_mfma_i32_16x16x64_i8 v[10:13], v[118:121], v[210:213], v[10:13]
	v_mfma_i32_16x16x64_i8 v[54:57], v[156:159], v[182:185], v[54:57]
	v_mfma_i32_16x16x64_i8 v[46:49], v[174:177], v[182:185], v[46:49]
	v_mfma_i32_16x16x64_i8 v[38:41], v[156:159], v[190:193], v[38:41]
	v_mfma_i32_16x16x64_i8 v[34:37], v[174:177], v[190:193], v[34:37]
	v_mfma_i32_16x16x64_i8 v[22:25], v[156:159], v[198:201], v[22:25]
	v_mfma_i32_16x16x64_i8 v[14:17], v[174:177], v[198:201], v[14:17]
	v_mfma_i32_16x16x64_i8 v[6:9], v[156:159], v[206:209], v[6:9]
	v_mfma_i32_16x16x64_i8 v[2:5], v[174:177], v[206:209], v[2:5]
	v_mfma_i32_16x16x64_i8 v[54:57], v[170:173], v[186:189], v[54:57]
	v_mfma_i32_16x16x64_i8 v[46:49], v[178:181], v[186:189], v[46:49]
	v_mfma_i32_16x16x64_i8 v[38:41], v[170:173], v[194:197], v[38:41]
	v_mfma_i32_16x16x64_i8 v[34:37], v[178:181], v[194:197], v[34:37]
	v_mfma_i32_16x16x64_i8 v[22:25], v[170:173], v[202:205], v[22:25]
	v_mfma_i32_16x16x64_i8 v[14:17], v[178:181], v[202:205], v[14:17]
	v_mfma_i32_16x16x64_i8 v[6:9], v[170:173], v[210:213], v[6:9]
	v_mfma_i32_16x16x64_i8 v[2:5], v[178:181], v[210:213], v[2:5]
	s_barrier
	s_setprio 0
	s_add_i32 s62, 0, 0x18000
	s_add_i32 s63, 0, 0x1c000
	v_add_u32_e32 v118, s62, v164
	v_add_u32_e32 v162, s63, v164
	ds_read_b128 v[102:105], v118
	ds_read_b128 v[106:109], v118 offset:1024
	ds_read_b128 v[114:117], v118 offset:2048
	ds_read_b128 v[118:121], v118 offset:3072
	ds_read_b128 v[156:159], v162
	ds_read_b128 v[170:173], v162 offset:1024
	ds_read_b128 v[174:177], v162 offset:2048
	ds_read_b128 v[178:181], v162 offset:3072
	s_add_u32 s36, s36, 0x80000
	s_addc_u32 s37, s37, 0
	s_mov_b32 m0, s45
	v_lshl_add_u64 v[220:221], s[36:37], 0, v[146:147]
	ds_read_b128 v[182:185], v168 offset:32768
	ds_read_b128 v[186:189], v168 offset:33792
	ds_read_b128 v[190:193], v168 offset:34816
	ds_read_b128 v[194:197], v168 offset:35840
	ds_read_b128 v[198:201], v168 offset:36864
	ds_read_b128 v[202:205], v168 offset:37888
	ds_read_b128 v[206:209], v168 offset:38912
	ds_read_b128 v[210:213], v168 offset:39936
	global_load_lds_dwordx4 v[220:221], off
	v_lshl_add_u64 v[220:221], s[36:37], 0, v[148:149]
	s_mov_b32 m0, s46
	s_nop 0
	global_load_lds_dwordx4 v[220:221], off
	s_waitcnt vmcnt(8)
	s_waitcnt lgkmcnt(0)
	s_setprio 1
	s_barrier
	s_waitcnt lgkmcnt(0)
	v_mfma_i32_16x16x64_i8 v[142:145], v[102:105], v[182:185], v[142:145]
	v_mfma_i32_16x16x64_i8 v[138:141], v[114:117], v[182:185], v[138:141]
	v_mfma_i32_16x16x64_i8 v[126:129], v[102:105], v[190:193], v[126:129]
	v_mfma_i32_16x16x64_i8 v[122:125], v[114:117], v[190:193], v[122:125]
	v_mfma_i32_16x16x64_i8 v[94:97], v[102:105], v[198:201], v[94:97]
	v_mfma_i32_16x16x64_i8 v[90:93], v[114:117], v[198:201], v[90:93]
	v_mfma_i32_16x16x64_i8 v[82:85], v[102:105], v[206:209], v[82:85]
	v_mfma_i32_16x16x64_i8 v[74:77], v[114:117], v[206:209], v[74:77]
	v_mfma_i32_16x16x64_i8 v[142:145], v[106:109], v[186:189], v[142:145]
	v_mfma_i32_16x16x64_i8 v[138:141], v[118:121], v[186:189], v[138:141]
	v_mfma_i32_16x16x64_i8 v[126:129], v[106:109], v[194:197], v[126:129]
	v_mfma_i32_16x16x64_i8 v[122:125], v[118:121], v[194:197], v[122:125]
	v_mfma_i32_16x16x64_i8 v[94:97], v[106:109], v[202:205], v[94:97]
	v_mfma_i32_16x16x64_i8 v[90:93], v[118:121], v[202:205], v[90:93]
	v_mfma_i32_16x16x64_i8 v[82:85], v[106:109], v[210:213], v[82:85]
	v_mfma_i32_16x16x64_i8 v[74:77], v[118:121], v[210:213], v[74:77]
	v_mfma_i32_16x16x64_i8 v[134:137], v[156:159], v[182:185], v[134:137]
	v_mfma_i32_16x16x64_i8 v[130:133], v[174:177], v[182:185], v[130:133]
	v_mfma_i32_16x16x64_i8 v[110:113], v[156:159], v[190:193], v[110:113]
	v_mfma_i32_16x16x64_i8 v[98:101], v[174:177], v[190:193], v[98:101]
	v_mfma_i32_16x16x64_i8 v[86:89], v[156:159], v[198:201], v[86:89]
	v_mfma_i32_16x16x64_i8 v[78:81], v[174:177], v[198:201], v[78:81]
	v_mfma_i32_16x16x64_i8 v[70:73], v[156:159], v[206:209], v[70:73]
	v_mfma_i32_16x16x64_i8 v[66:69], v[174:177], v[206:209], v[66:69]
	v_mfma_i32_16x16x64_i8 v[134:137], v[170:173], v[186:189], v[134:137]
	v_mfma_i32_16x16x64_i8 v[130:133], v[178:181], v[186:189], v[130:133]
	v_mfma_i32_16x16x64_i8 v[110:113], v[170:173], v[194:197], v[110:113]
	v_mfma_i32_16x16x64_i8 v[98:101], v[178:181], v[194:197], v[98:101]
	v_mfma_i32_16x16x64_i8 v[86:89], v[170:173], v[202:205], v[86:89]
	v_mfma_i32_16x16x64_i8 v[78:81], v[178:181], v[202:205], v[78:81]
	v_mfma_i32_16x16x64_i8 v[70:73], v[170:173], v[210:213], v[70:73]
	v_mfma_i32_16x16x64_i8 v[66:69], v[178:181], v[210:213], v[66:69]
	s_barrier
; #define PG8_STAGE(bufoff, gbase, voff) do { _Pragma("unroll") for (int _i = 0; _i < 2; ++_i) \
;         __builtin_amdgcn_global_load_lds((const unsigned*)((const char*)(gbase) + (voff)[_i]), (LAS unsigned*)(lds + (bufoff) + ldsw + _i * 8192), 16, 0, 0); } while (0)
; #define PG8_LDA(dst, b, h) do { _Pragma("unroll") for (int m = 0; m < 4; ++m) _Pragma("unroll") for (int k = 0; k < 2; ++k) dst[m][k] = *(const LAS bf16x8*)(lds + PG8_SA(b, h) + aoff + m * 2048 + k * 1024); } while (0)
; #define PG8_WAIT_V(n) asm volatile("s_waitcnt vmcnt(" #n ")" ::: "memory")
; #define PG8_WAIT_L(n) asm volatile("s_waitcnt lgkmcnt(" #n ")" ::: "memory")
; #define PG8_BAR __builtin_amdgcn_s_barrier()
; #define PG8_SCHED __builtin_amdgcn_sched_barrier(0)
; template <class Epi, class Geom, class Sched, bool ALIGN_EPI, bool I8 = false>
; __device__ __forceinline__ void gemm_phase(LAS unsigned char* lds, const Gemm g, const Sched& S, const Epi& E) {
;     ...
;             PG8_LDA(At, 1, 1); PG8_STAGE(PG8_SB(1, 0), b3, voffB); PG8_STAGE(PG8_SB(1, 1), b3 + hsB, voffB); PG8_STAGE(PG8_SA(1, 0), a3, voffA);
;             PG8_WAIT_V(8); PG8_WAIT_L(0); PG8_BAR; PG8_MMA(1, 0, At, B0); PG8_MMA(1, 1, At, B1); PG8_BAR; PG8_SCHED;
;         }
;         if constexpr (ALIGN_EPI) { if (wr == 0) PG8_BAR; }
	s_setprio 0
	s_add_i32 s36, s62, s41
	v_lshl_add_u64 v[160:161], v[160:161], 0, s[16:17]
	s_mov_b32 m0, s36
	ds_read_b128 v[182:185], v168 offset:49152
	ds_read_b128 v[186:189], v168 offset:50176
	ds_read_b128 v[190:193], v168 offset:51200
	ds_read_b128 v[194:197], v168 offset:52224
	ds_read_b128 v[198:201], v168 offset:53248
	ds_read_b128 v[202:205], v168 offset:54272
	ds_read_b128 v[206:209], v168 offset:55296
	ds_read_b128 v[210:213], v168 offset:56320
	global_load_lds_dwordx4 v[160:161], off
	s_add_i32 m0, s36, 0x2000
	s_add_u32 s34, s34, 0x80080
	v_lshl_add_u64 v[160:161], v[214:215], 0, s[16:17]
	s_addc_u32 s35, s35, 0
	s_add_i32 s36, s63, s41
	global_load_lds_dwordx4 v[160:161], off
	v_lshl_add_u64 v[160:161], s[34:35], 0, v[146:147]
	s_mov_b32 m0, s36
	s_nop 0
	global_load_lds_dwordx4 v[160:161], off
	v_lshl_add_u64 v[160:161], s[34:35], 0, v[148:149]
	s_add_i32 m0, s36, 0x2000
	s_nop 0
	global_load_lds_dwordx4 v[160:161], off
	v_lshl_add_u64 v[160:161], v[216:217], 0, s[16:17]
	s_mov_b32 m0, s47
	s_nop 0
	global_load_lds_dwordx4 v[160:161], off
	v_lshl_add_u64 v[160:161], v[218:219], 0, s[16:17]
	s_mov_b32 m0, s48
	s_nop 0
	global_load_lds_dwordx4 v[160:161], off
	s_waitcnt vmcnt(8)
	s_waitcnt lgkmcnt(0)
	s_setprio 1
	s_barrier
	s_waitcnt lgkmcnt(0)
	v_mfma_i32_16x16x64_i8 v[62:65], v[102:105], v[182:185], v[62:65]
	v_mfma_i32_16x16x64_i8 v[58:61], v[114:117], v[182:185], v[58:61]
	v_mfma_i32_16x16x64_i8 v[50:53], v[102:105], v[190:193], v[50:53]
	v_mfma_i32_16x16x64_i8 v[42:45], v[114:117], v[190:193], v[42:45]
	v_mfma_i32_16x16x64_i8 v[30:33], v[102:105], v[198:201], v[30:33]
	v_mfma_i32_16x16x64_i8 v[26:29], v[114:117], v[198:201], v[26:29]
	v_mfma_i32_16x16x64_i8 v[18:21], v[102:105], v[206:209], v[18:21]
	v_mfma_i32_16x16x64_i8 v[10:13], v[114:117], v[206:209], v[10:13]
	v_mfma_i32_16x16x64_i8 v[62:65], v[106:109], v[186:189], v[62:65]
	v_mfma_i32_16x16x64_i8 v[58:61], v[118:121], v[186:189], v[58:61]
	v_mfma_i32_16x16x64_i8 v[50:53], v[106:109], v[194:197], v[50:53]
	v_mfma_i32_16x16x64_i8 v[42:45], v[118:121], v[194:197], v[42:45]
	v_mfma_i32_16x16x64_i8 v[30:33], v[106:109], v[202:205], v[30:33]
	v_mfma_i32_16x16x64_i8 v[26:29], v[118:121], v[202:205], v[26:29]
	v_mfma_i32_16x16x64_i8 v[18:21], v[106:109], v[210:213], v[18:21]
	v_mfma_i32_16x16x64_i8 v[10:13], v[118:121], v[210:213], v[10:13]
	v_mfma_i32_16x16x64_i8 v[54:57], v[156:159], v[182:185], v[54:57]
	v_mfma_i32_16x16x64_i8 v[46:49], v[174:177], v[182:185], v[46:49]
	v_mfma_i32_16x16x64_i8 v[38:41], v[156:159], v[190:193], v[38:41]
	v_mfma_i32_16x16x64_i8 v[34:37], v[174:177], v[190:193], v[34:37]
	v_mfma_i32_16x16x64_i8 v[22:25], v[156:159], v[198:201], v[22:25]
	v_mfma_i32_16x16x64_i8 v[14:17], v[174:177], v[198:201], v[14:17]
	v_mfma_i32_16x16x64_i8 v[6:9], v[156:159], v[206:209], v[6:9]
	v_mfma_i32_16x16x64_i8 v[2:5], v[174:177], v[206:209], v[2:5]
	v_mfma_i32_16x16x64_i8 v[54:57], v[170:173], v[186:189], v[54:57]
	v_mfma_i32_16x16x64_i8 v[46:49], v[178:181], v[186:189], v[46:49]
	v_mfma_i32_16x16x64_i8 v[38:41], v[170:173], v[194:197], v[38:41]
	v_mfma_i32_16x16x64_i8 v[34:37], v[178:181], v[194:197], v[34:37]
	v_mfma_i32_16x16x64_i8 v[22:25], v[170:173], v[202:205], v[22:25]
	v_mfma_i32_16x16x64_i8 v[14:17], v[178:181], v[202:205], v[14:17]
	v_mfma_i32_16x16x64_i8 v[6:9], v[170:173], v[210:213], v[6:9]
	v_mfma_i32_16x16x64_i8 v[2:5], v[178:181], v[210:213], v[2:5]
	s_barrier
	s_setprio 0
	s_add_i32 s61, s61, 2
	s_add_u32 s30, s30, 0x100
	s_addc_u32 s31, s31, 0
	s_add_u32 s59, s59, 0x100
	s_addc_u32 s60, s60, 0
	s_cmp_gt_u32 s61, 29
	s_cbranch_scc0 .LBB0_2231
	s_and_b64 vcc, exec, s[18:19]
	s_cbranch_vccz .LBB0_2234
	s_barrier

; #define PG8_STAGE(bufoff, gbase, voff) do { _Pragma("unroll") for (int _i = 0; _i < 2; ++_i) \
;         __builtin_amdgcn_global_load_lds((const unsigned*)((const char*)(gbase) + (voff)[_i]), (LAS unsigned*)(lds + (bufoff) + ldsw + _i * 8192), 16, 0, 0); } while (0)
; #define PG8_LDA(dst, b, h) do { _Pragma("unroll") for (int m = 0; m < 4; ++m) _Pragma("unroll") for (int k = 0; k < 2; ++k) dst[m][k] = *(const LAS bf16x8*)(lds + PG8_SA(b, h) + aoff + m * 2048 + k * 1024); } while (0)
; #define PG8_LDB(dst, b, h) do { _Pragma("unroll") for (int n = 0; n < 2; ++n) _Pragma("unroll") for (int k = 0; k < 2; ++k) dst[n][k] = *(const LAS bf16x8*)(lds + PG8_SB(b, h) + boff + n * 2048 + k * 1024); } while (0)
; #define PG8_WAIT_V(n) asm volatile("s_waitcnt vmcnt(" #n ")" ::: "memory")
; #define PG8_WAIT_L(n) asm volatile("s_waitcnt lgkmcnt(" #n ")" ::: "memory")
; #define PG8_BAR __builtin_amdgcn_s_barrier()
; #define PG8_SCHED __builtin_amdgcn_sched_barrier(0)
; template <class Epi, class Geom, class Sched, bool ALIGN_EPI, bool I8 = false>
; __device__ __forceinline__ void gemm_phase(LAS unsigned char* lds, const Gemm g, const Sched& S, const Epi& E) {
;     ...
;         for (int t = 0; t < nt; t += 2) {
;             const bool last = (t == nt - 2);
;             const char* a1 = cA + (size_t)(t + 1) * kstep;
;             const char* a2 = last ? nA : cA + (size_t)(t + 2) * kstep; const char* b2 = last ? nB : cB + (size_t)(t + 2) * kstep;
;             const char* a3 = a2 + kstep; const char* b3 = b2 + kstep;
;             PG8_LDB(B0, 0, 0); PG8_LDB(B1, 0, 1); PG8_SCHED; PG8_LDA(At, 0, 0); PG8_STAGE(PG8_SA(1, 1), a1 + hsA, voffA);
;             PG8_WAIT_V(8); PG8_WAIT_L(0); PG8_BAR; PG8_MMA(0, 0, At, B0); PG8_MMA(0, 1, At, B1); PG8_BAR; PG8_SCHED;
;             PG8_LDA(At, 0, 1); PG8_STAGE(PG8_SB(0, 0), b2, voffB); PG8_STAGE(PG8_SB(0, 1), b2 + hsB, voffB); PG8_STAGE(PG8_SA(0, 0), a2, voffA);
;             PG8_WAIT_V(8); PG8_WAIT_L(0); PG8_BAR; PG8_MMA(1, 0, At, B0); PG8_MMA(1, 1, At, B1); PG8_BAR; PG8_SCHED;
.LBB0_2243:
	s_add_i32 s20, s24, 0x100
	s_and_b64 s[18:19], s[18:19], exec
	s_cselect_b32 s19, 0, s20
	s_cselect_b32 s18, 0, 0
	s_add_u32 s20, s10, s19
	s_addc_u32 s21, s11, s18
	s_add_u32 s22, s4, s19
	v_add_u32_e32 v127, s41, v1
	s_addc_u32 s23, s5, s18
	ds_read_b128 v[128:131], v127
	ds_read_b128 v[132:135], v127 offset:1024
	ds_read_b128 v[136:139], v127 offset:2048
	ds_read_b128 v[152:155], v127 offset:3072
	v_add_u32_e32 v127, s42, v1
	s_add_u32 s28, s12, s24
	ds_read_b128 v[156:159], v127
	ds_read_b128 v[160:163], v127 offset:1024
	ds_read_b128 v[164:167], v127 offset:2048
	ds_read_b128 v[168:171], v127 offset:3072
	s_addc_u32 s29, s13, 0
	s_add_u32 s24, s22, 0x80000
	s_addc_u32 s25, s23, 0
	s_add_u32 s18, s20, 0x80000
	s_addc_u32 s19, s21, 0
	s_add_u32 s26, s22, 0x80080
	s_addc_u32 s27, s23, 0
	v_lshl_add_u64 v[140:141], s[28:29], 0, v[146:147]
	s_mov_b32 m0, s43
	v_lshl_add_u64 v[140:141], v[140:141], 0, s[14:15]
	ds_read_b128 v[172:175], v126
	ds_read_b128 v[176:179], v126 offset:1024
	ds_read_b128 v[180:183], v126 offset:2048
	ds_read_b128 v[184:187], v126 offset:3072
	ds_read_b128 v[188:191], v126 offset:4096
	ds_read_b128 v[192:195], v126 offset:5120
	ds_read_b128 v[196:199], v126 offset:6144
	ds_read_b128 v[200:203], v126 offset:7168
	global_load_lds_dwordx4 v[140:141], off
	v_lshl_add_u64 v[140:141], s[28:29], 0, v[148:149]
	v_lshl_add_u64 v[140:141], v[140:141], 0, s[14:15]
	s_mov_b32 m0, s44
	s_nop 0
	global_load_lds_dwordx4 v[140:141], off
	s_waitcnt vmcnt(8)
	s_waitcnt lgkmcnt(0)
	s_setprio 1
	s_barrier
	s_waitcnt lgkmcnt(0)
	v_mfma_i32_16x16x64_i8 v[140:143], v[128:131], v[172:175], v[142:145]
	v_mfma_i32_16x16x64_i8 v[122:125], v[136:139], v[172:175], v[122:125]
	v_mfma_i32_16x16x64_i8 v[110:113], v[128:131], v[180:183], v[110:113]
	v_mfma_i32_16x16x64_i8 v[106:109], v[136:139], v[180:183], v[106:109]
	v_mfma_i32_16x16x64_i8 v[94:97], v[128:131], v[188:191], v[94:97]
	v_mfma_i32_16x16x64_i8 v[90:93], v[136:139], v[188:191], v[90:93]
	v_mfma_i32_16x16x64_i8 v[78:81], v[128:131], v[196:199], v[78:81]
	v_mfma_i32_16x16x64_i8 v[74:77], v[136:139], v[196:199], v[74:77]
	v_mfma_i32_16x16x64_i8 v[140:143], v[132:135], v[176:179], v[140:143]
	v_mfma_i32_16x16x64_i8 v[122:125], v[152:155], v[176:179], v[122:125]
	v_mfma_i32_16x16x64_i8 v[110:113], v[132:135], v[184:187], v[110:113]
	v_mfma_i32_16x16x64_i8 v[106:109], v[152:155], v[184:187], v[106:109]
	v_mfma_i32_16x16x64_i8 v[94:97], v[132:135], v[192:195], v[94:97]
	v_mfma_i32_16x16x64_i8 v[90:93], v[152:155], v[192:195], v[90:93]
	v_mfma_i32_16x16x64_i8 v[78:81], v[132:135], v[200:203], v[78:81]
	v_mfma_i32_16x16x64_i8 v[74:77], v[152:155], v[200:203], v[74:77]
	v_mfma_i32_16x16x64_i8 v[118:121], v[156:159], v[172:175], v[118:121]
	v_mfma_i32_16x16x64_i8 v[114:117], v[164:167], v[172:175], v[114:117]
	v_mfma_i32_16x16x64_i8 v[102:105], v[156:159], v[180:183], v[102:105]
	v_mfma_i32_16x16x64_i8 v[98:101], v[164:167], v[180:183], v[98:101]
	v_mfma_i32_16x16x64_i8 v[86:89], v[156:159], v[188:191], v[86:89]
	v_mfma_i32_16x16x64_i8 v[82:85], v[164:167], v[188:191], v[82:85]
	v_mfma_i32_16x16x64_i8 v[70:73], v[156:159], v[196:199], v[70:73]
	v_mfma_i32_16x16x64_i8 v[66:69], v[164:167], v[196:199], v[66:69]
	v_mfma_i32_16x16x64_i8 v[118:121], v[160:163], v[176:179], v[118:121]
	v_mfma_i32_16x16x64_i8 v[114:117], v[168:171], v[176:179], v[114:117]
	v_mfma_i32_16x16x64_i8 v[102:105], v[160:163], v[184:187], v[102:105]
	v_mfma_i32_16x16x64_i8 v[98:101], v[168:171], v[184:187], v[98:101]
	v_mfma_i32_16x16x64_i8 v[86:89], v[160:163], v[192:195], v[86:89]
	v_mfma_i32_16x16x64_i8 v[82:85], v[168:171], v[192:195], v[82:85]
	v_mfma_i32_16x16x64_i8 v[70:73], v[160:163], v[200:203], v[70:73]
	v_mfma_i32_16x16x64_i8 v[66:69], v[168:171], v[200:203], v[66:69]
	s_barrier
	s_setprio 0
	s_mov_b32 m0, s45
	v_lshl_add_u64 v[204:205], s[22:23], 0, v[146:147]
	ds_read_b128 v[172:175], v126 offset:16384
	ds_read_b128 v[176:179], v126 offset:17408
	ds_read_b128 v[180:183], v126 offset:18432
	ds_read_b128 v[184:187], v126 offset:19456
	ds_read_b128 v[188:191], v126 offset:20480
	ds_read_b128 v[192:195], v126 offset:21504
	ds_read_b128 v[196:199], v126 offset:22528
	ds_read_b128 v[200:203], v126 offset:23552
	global_load_lds_dwordx4 v[204:205], off
	v_lshl_add_u64 v[206:207], s[22:23], 0, v[148:149]
	s_mov_b32 m0, s46
	v_lshl_add_u64 v[144:145], s[24:25], 0, v[146:147]
	global_load_lds_dwordx4 v[206:207], off
	s_mov_b32 m0, s47
	v_lshl_add_u64 v[208:209], s[20:21], 0, v[146:147]
	global_load_lds_dwordx4 v[144:145], off
	v_lshl_add_u64 v[144:145], s[24:25], 0, v[148:149]
	s_mov_b32 m0, s48
	v_lshl_add_u64 v[210:211], s[20:21], 0, v[148:149]
	global_load_lds_dwordx4 v[144:145], off
	s_mov_b32 m0, s36
	s_nop 0
	global_load_lds_dwordx4 v[208:209], off
	s_mov_b32 m0, s33
	s_nop 0
	global_load_lds_dwordx4 v[210:211], off
	s_waitcnt vmcnt(8)
	s_waitcnt lgkmcnt(0)
	s_setprio 1
	s_barrier
; #define PG8_STAGE(bufoff, gbase, voff) do { _Pragma("unroll") for (int _i = 0; _i < 2; ++_i) \
;         __builtin_amdgcn_global_load_lds((const unsigned*)((const char*)(gbase) + (voff)[_i]), (LAS unsigned*)(lds + (bufoff) + ldsw + _i * 8192), 16, 0, 0); } while (0)
; #define PG8_LDA(dst, b, h) do { _Pragma("unroll") for (int m = 0; m < 4; ++m) _Pragma("unroll") for (int k = 0; k < 2; ++k) dst[m][k] = *(const LAS bf16x8*)(lds + PG8_SA(b, h) + aoff + m * 2048 + k * 1024); } while (0)
; #define PG8_LDB(dst, b, h) do { _Pragma("unroll") for (int n = 0; n < 2; ++n) _Pragma("unroll") for (int k = 0; k < 2; ++k) dst[n][k] = *(const LAS bf16x8*)(lds + PG8_SB(b, h) + boff + n * 2048 + k * 1024); } while (0)
; #define PG8_WAIT_V(n) asm volatile("s_waitcnt vmcnt(" #n ")" ::: "memory")
; template <class Epi, class Geom, class Sched, bool ALIGN_EPI, bool I8 = false>
; __device__ __forceinline__ void gemm_phase(LAS unsigned char* lds, const Gemm g, const Sched& S, const Epi& E) {
;     ...
;         for (int t = 0; t < nt; t += 2) {
;             const bool last = (t == nt - 2);
;             const char* a1 = cA + (size_t)(t + 1) * kstep;
;             const char* a2 = last ? nA : cA + (size_t)(t + 2) * kstep; const char* b2 = last ? nB : cB + (size_t)(t + 2) * kstep;
;             const char* a3 = a2 + kstep; const char* b3 = b2 + kstep;
;             PG8_LDB(B0, 0, 0); PG8_LDB(B1, 0, 1); PG8_SCHED; PG8_LDA(At, 0, 0); PG8_STAGE(PG8_SA(1, 1), a1 + hsA, voffA);
;             PG8_WAIT_V(8); PG8_WAIT_L(0); PG8_BAR; PG8_MMA(0, 0, At, B0); PG8_MMA(0, 1, At, B1); PG8_BAR; PG8_SCHED;
;             PG8_LDA(At, 0, 1); PG8_STAGE(PG8_SB(0, 0), b2, voffB); PG8_STAGE(PG8_SB(0, 1), b2 + hsB, voffB); PG8_STAGE(PG8_SA(0, 0), a2, voffA);
;             PG8_WAIT_V(8); PG8_WAIT_L(0); PG8_BAR; PG8_MMA(1, 0, At, B0); PG8_MMA(1, 1, At, B1); PG8_BAR; PG8_SCHED;
;             PG8_LDB(B0, 1, 0); PG8_LDB(B1, 1, 1); PG8_SCHED; PG8_LDA(At, 1, 0); PG8_STAGE(PG8_SA(0, 1), a2 + hsA, voffA);
;             PG8_WAIT_V(8); PG8_WAIT_L(0); PG8_BAR; PG8_MMA(0, 0, At, B0); PG8_MMA(0, 1, At, B1); PG8_BAR; PG8_SCHED;
;             PG8_LDA(At, 1, 1); PG8_STAGE(PG8_SB(1, 0), b3, voffB); PG8_STAGE(PG8_SB(1, 1), b3 + hsB, voffB); PG8_STAGE(PG8_SA(1, 0), a3, voffA);
;             PG8_WAIT_V(8); PG8_WAIT_L(0); PG8_BAR; PG8_MMA(1, 0, At, B0); PG8_MMA(1, 1, At, B1); PG8_BAR; PG8_SCHED;
	s_waitcnt lgkmcnt(0)
	v_mfma_i32_16x16x64_i8 v[62:65], v[128:131], v[172:175], v[62:65]
	v_mfma_i32_16x16x64_i8 v[58:61], v[136:139], v[172:175], v[58:61]
	v_mfma_i32_16x16x64_i8 v[46:49], v[128:131], v[180:183], v[46:49]
	v_mfma_i32_16x16x64_i8 v[42:45], v[136:139], v[180:183], v[42:45]
	v_mfma_i32_16x16x64_i8 v[30:33], v[128:131], v[188:191], v[30:33]
	v_mfma_i32_16x16x64_i8 v[26:29], v[136:139], v[188:191], v[26:29]
	v_mfma_i32_16x16x64_i8 v[14:17], v[128:131], v[196:199], v[14:17]
	v_mfma_i32_16x16x64_i8 v[10:13], v[136:139], v[196:199], v[10:13]
	v_mfma_i32_16x16x64_i8 v[62:65], v[132:135], v[176:179], v[62:65]
	v_mfma_i32_16x16x64_i8 v[58:61], v[152:155], v[176:179], v[58:61]
	v_mfma_i32_16x16x64_i8 v[46:49], v[132:135], v[184:187], v[46:49]
	v_mfma_i32_16x16x64_i8 v[42:45], v[152:155], v[184:187], v[42:45]
	v_mfma_i32_16x16x64_i8 v[30:33], v[132:135], v[192:195], v[30:33]
	v_mfma_i32_16x16x64_i8 v[26:29], v[152:155], v[192:195], v[26:29]
	v_mfma_i32_16x16x64_i8 v[14:17], v[132:135], v[200:203], v[14:17]
	v_mfma_i32_16x16x64_i8 v[10:13], v[152:155], v[200:203], v[10:13]
	v_mfma_i32_16x16x64_i8 v[54:57], v[156:159], v[172:175], v[54:57]
	v_mfma_i32_16x16x64_i8 v[50:53], v[164:167], v[172:175], v[50:53]
	v_mfma_i32_16x16x64_i8 v[38:41], v[156:159], v[180:183], v[38:41]
	v_mfma_i32_16x16x64_i8 v[34:37], v[164:167], v[180:183], v[34:37]
	v_mfma_i32_16x16x64_i8 v[22:25], v[156:159], v[188:191], v[22:25]
	v_mfma_i32_16x16x64_i8 v[18:21], v[164:167], v[188:191], v[18:21]
	v_mfma_i32_16x16x64_i8 v[6:9], v[156:159], v[196:199], v[6:9]
	v_mfma_i32_16x16x64_i8 v[2:5], v[164:167], v[196:199], v[2:5]
	v_mfma_i32_16x16x64_i8 v[54:57], v[160:163], v[176:179], v[54:57]
	v_mfma_i32_16x16x64_i8 v[50:53], v[168:171], v[176:179], v[50:53]
	v_mfma_i32_16x16x64_i8 v[38:41], v[160:163], v[184:187], v[38:41]
	v_mfma_i32_16x16x64_i8 v[34:37], v[168:171], v[184:187], v[34:37]
	v_mfma_i32_16x16x64_i8 v[22:25], v[160:163], v[192:195], v[22:25]
	v_mfma_i32_16x16x64_i8 v[18:21], v[168:171], v[192:195], v[18:21]
	v_mfma_i32_16x16x64_i8 v[6:9], v[160:163], v[200:203], v[6:9]
	v_mfma_i32_16x16x64_i8 v[2:5], v[168:171], v[200:203], v[2:5]
	s_barrier
	s_setprio 0
	v_add_u32_e32 v127, s49, v1
	ds_read_b128 v[128:131], v127
	ds_read_b128 v[132:135], v127 offset:1024
	ds_read_b128 v[136:139], v127 offset:2048
	ds_read_b128 v[152:155], v127 offset:3072
	v_add_u32_e32 v127, s50, v1
	ds_read_b128 v[156:159], v127
	ds_read_b128 v[160:163], v127 offset:1024
	ds_read_b128 v[164:167], v127 offset:2048
	ds_read_b128 v[168:171], v127 offset:3072
	s_mov_b32 m0, s37
	v_lshl_add_u64 v[144:145], s[18:19], 0, v[146:147]
	ds_read_b128 v[172:175], v126 offset:32768
	ds_read_b128 v[176:179], v126 offset:33792
	ds_read_b128 v[180:183], v126 offset:34816
	ds_read_b128 v[184:187], v126 offset:35840
	ds_read_b128 v[188:191], v126 offset:36864
	ds_read_b128 v[192:195], v126 offset:37888
	ds_read_b128 v[196:199], v126 offset:38912
	ds_read_b128 v[200:203], v126 offset:39936
	global_load_lds_dwordx4 v[144:145], off
	v_lshl_add_u64 v[144:145], s[18:19], 0, v[148:149]
	s_mov_b32 m0, s38
	s_nop 0
	global_load_lds_dwordx4 v[144:145], off
	s_waitcnt vmcnt(8)
	s_waitcnt lgkmcnt(0)
	s_setprio 1
	s_barrier
	s_waitcnt lgkmcnt(0)
	v_mfma_i32_16x16x64_i8 v[140:143], v[128:131], v[172:175], v[140:143]
	v_mfma_i32_16x16x64_i8 v[122:125], v[136:139], v[172:175], v[122:125]
	v_mfma_i32_16x16x64_i8 v[110:113], v[128:131], v[180:183], v[110:113]
	v_mfma_i32_16x16x64_i8 v[106:109], v[136:139], v[180:183], v[106:109]
	v_mfma_i32_16x16x64_i8 v[94:97], v[128:131], v[188:191], v[94:97]
	v_mfma_i32_16x16x64_i8 v[90:93], v[136:139], v[188:191], v[90:93]
	v_mfma_i32_16x16x64_i8 v[78:81], v[128:131], v[196:199], v[78:81]
	v_mfma_i32_16x16x64_i8 v[74:77], v[136:139], v[196:199], v[74:77]
	v_mfma_i32_16x16x64_i8 v[142:145], v[132:135], v[176:179], v[140:143]
	v_mfma_i32_16x16x64_i8 v[122:125], v[152:155], v[176:179], v[122:125]
	v_mfma_i32_16x16x64_i8 v[110:113], v[132:135], v[184:187], v[110:113]
	v_mfma_i32_16x16x64_i8 v[106:109], v[152:155], v[184:187], v[106:109]
	v_mfma_i32_16x16x64_i8 v[94:97], v[132:135], v[192:195], v[94:97]
	v_mfma_i32_16x16x64_i8 v[90:93], v[152:155], v[192:195], v[90:93]
	v_mfma_i32_16x16x64_i8 v[78:81], v[132:135], v[200:203], v[78:81]
	v_mfma_i32_16x16x64_i8 v[74:77], v[152:155], v[200:203], v[74:77]
	v_mfma_i32_16x16x64_i8 v[118:121], v[156:159], v[172:175], v[118:121]
	v_mfma_i32_16x16x64_i8 v[114:117], v[164:167], v[172:175], v[114:117]
	v_mfma_i32_16x16x64_i8 v[102:105], v[156:159], v[180:183], v[102:105]
	v_mfma_i32_16x16x64_i8 v[98:101], v[164:167], v[180:183], v[98:101]
	v_mfma_i32_16x16x64_i8 v[86:89], v[156:159], v[188:191], v[86:89]
	v_mfma_i32_16x16x64_i8 v[82:85], v[164:167], v[188:191], v[82:85]
	v_mfma_i32_16x16x64_i8 v[70:73], v[156:159], v[196:199], v[70:73]
	v_mfma_i32_16x16x64_i8 v[66:69], v[164:167], v[196:199], v[66:69]
	v_mfma_i32_16x16x64_i8 v[118:121], v[160:163], v[176:179], v[118:121]
	v_mfma_i32_16x16x64_i8 v[114:117], v[168:171], v[176:179], v[114:117]
	v_mfma_i32_16x16x64_i8 v[102:105], v[160:163], v[184:187], v[102:105]
	v_mfma_i32_16x16x64_i8 v[98:101], v[168:171], v[184:187], v[98:101]
	v_mfma_i32_16x16x64_i8 v[86:89], v[160:163], v[192:195], v[86:89]
	v_mfma_i32_16x16x64_i8 v[82:85], v[168:171], v[192:195], v[82:85]
	v_mfma_i32_16x16x64_i8 v[70:73], v[160:163], v[200:203], v[70:73]
	v_mfma_i32_16x16x64_i8 v[66:69], v[168:171], v[200:203], v[66:69]
	s_barrier
; #define PG8_STAGE(bufoff, gbase, voff) do { _Pragma("unroll") for (int _i = 0; _i < 2; ++_i) \
;         __builtin_amdgcn_global_load_lds((const unsigned*)((const char*)(gbase) + (voff)[_i]), (LAS unsigned*)(lds + (bufoff) + ldsw + _i * 8192), 16, 0, 0); } while (0)
; #define PG8_LDA(dst, b, h) do { _Pragma("unroll") for (int m = 0; m < 4; ++m) _Pragma("unroll") for (int k = 0; k < 2; ++k) dst[m][k] = *(const LAS bf16x8*)(lds + PG8_SA(b, h) + aoff + m * 2048 + k * 1024); } while (0)
; #define PG8_WAIT_V(n) asm volatile("s_waitcnt vmcnt(" #n ")" ::: "memory")
; #define PG8_WAIT_L(n) asm volatile("s_waitcnt lgkmcnt(" #n ")" ::: "memory")
; #define PG8_BAR __builtin_amdgcn_s_barrier()
; #define PG8_SCHED __builtin_amdgcn_sched_barrier(0)
; template <class Epi, class Geom, class Sched, bool ALIGN_EPI, bool I8 = false>
; __device__ __forceinline__ void gemm_phase(LAS unsigned char* lds, const Gemm g, const Sched& S, const Epi& E) {
;     ...
;             PG8_LDA(At, 1, 1); PG8_STAGE(PG8_SB(1, 0), b3, voffB); PG8_STAGE(PG8_SB(1, 1), b3 + hsB, voffB); PG8_STAGE(PG8_SA(1, 0), a3, voffA);
;             PG8_WAIT_V(8); PG8_WAIT_L(0); PG8_BAR; PG8_MMA(1, 0, At, B0); PG8_MMA(1, 1, At, B1); PG8_BAR; PG8_SCHED;
;         }
;         if constexpr (ALIGN_EPI) { if (wr == 0) PG8_BAR; }
;         E(acc, cur, wr, wc, fr, fq);
;         if (!has_next) break;
	s_setprio 0
	s_mov_b32 m0, s51
	v_lshl_add_u64 v[140:141], v[204:205], 0, s[14:15]
	ds_read_b128 v[172:175], v126 offset:49152
	ds_read_b128 v[176:179], v126 offset:50176
	ds_read_b128 v[180:183], v126 offset:51200
	ds_read_b128 v[184:187], v126 offset:52224
	ds_read_b128 v[188:191], v126 offset:53248
	ds_read_b128 v[192:195], v126 offset:54272
	ds_read_b128 v[196:199], v126 offset:55296
	ds_read_b128 v[200:203], v126 offset:56320
	global_load_lds_dwordx4 v[140:141], off
	v_lshl_add_u64 v[140:141], v[206:207], 0, s[14:15]
	s_mov_b32 m0, s52
	s_nop 0
	global_load_lds_dwordx4 v[140:141], off
	v_lshl_add_u64 v[140:141], s[26:27], 0, v[146:147]
	s_mov_b32 m0, s53
	s_nop 0
	global_load_lds_dwordx4 v[140:141], off
	v_lshl_add_u64 v[140:141], s[26:27], 0, v[148:149]
	s_mov_b32 m0, s54
	s_nop 0
	global_load_lds_dwordx4 v[140:141], off
	v_lshl_add_u64 v[140:141], v[208:209], 0, s[14:15]
	s_mov_b32 m0, s39
	s_nop 0
	global_load_lds_dwordx4 v[140:141], off
	v_lshl_add_u64 v[140:141], v[210:211], 0, s[14:15]
	s_mov_b32 m0, s40
	s_nop 0
	global_load_lds_dwordx4 v[140:141], off
	s_waitcnt vmcnt(8)
	s_waitcnt lgkmcnt(0)
	s_setprio 1
	s_barrier
	s_waitcnt lgkmcnt(0)
	v_mfma_i32_16x16x64_i8 v[62:65], v[128:131], v[172:175], v[62:65]
	v_mfma_i32_16x16x64_i8 v[58:61], v[136:139], v[172:175], v[58:61]
	v_mfma_i32_16x16x64_i8 v[46:49], v[128:131], v[180:183], v[46:49]
	v_mfma_i32_16x16x64_i8 v[42:45], v[136:139], v[180:183], v[42:45]
	v_mfma_i32_16x16x64_i8 v[30:33], v[128:131], v[188:191], v[30:33]
	v_mfma_i32_16x16x64_i8 v[26:29], v[136:139], v[188:191], v[26:29]
	v_mfma_i32_16x16x64_i8 v[14:17], v[128:131], v[196:199], v[14:17]
	v_mfma_i32_16x16x64_i8 v[10:13], v[136:139], v[196:199], v[10:13]
	v_mfma_i32_16x16x64_i8 v[62:65], v[132:135], v[176:179], v[62:65]
	v_mfma_i32_16x16x64_i8 v[58:61], v[152:155], v[176:179], v[58:61]
	v_mfma_i32_16x16x64_i8 v[46:49], v[132:135], v[184:187], v[46:49]
	v_mfma_i32_16x16x64_i8 v[42:45], v[152:155], v[184:187], v[42:45]
	v_mfma_i32_16x16x64_i8 v[30:33], v[132:135], v[192:195], v[30:33]
	v_mfma_i32_16x16x64_i8 v[26:29], v[152:155], v[192:195], v[26:29]
	v_mfma_i32_16x16x64_i8 v[14:17], v[132:135], v[200:203], v[14:17]
	v_mfma_i32_16x16x64_i8 v[10:13], v[152:155], v[200:203], v[10:13]
	v_mfma_i32_16x16x64_i8 v[54:57], v[156:159], v[172:175], v[54:57]
	v_mfma_i32_16x16x64_i8 v[50:53], v[164:167], v[172:175], v[50:53]
	v_mfma_i32_16x16x64_i8 v[38:41], v[156:159], v[180:183], v[38:41]
	v_mfma_i32_16x16x64_i8 v[34:37], v[164:167], v[180:183], v[34:37]
	v_mfma_i32_16x16x64_i8 v[22:25], v[156:159], v[188:191], v[22:25]
	v_mfma_i32_16x16x64_i8 v[18:21], v[164:167], v[188:191], v[18:21]
	v_mfma_i32_16x16x64_i8 v[6:9], v[156:159], v[196:199], v[6:9]
	v_mfma_i32_16x16x64_i8 v[2:5], v[164:167], v[196:199], v[2:5]
	v_mfma_i32_16x16x64_i8 v[54:57], v[160:163], v[176:179], v[54:57]
	v_mfma_i32_16x16x64_i8 v[50:53], v[168:171], v[176:179], v[50:53]
	v_mfma_i32_16x16x64_i8 v[38:41], v[160:163], v[184:187], v[38:41]
	v_mfma_i32_16x16x64_i8 v[34:37], v[168:171], v[184:187], v[34:37]
	v_mfma_i32_16x16x64_i8 v[22:25], v[160:163], v[192:195], v[22:25]
	v_mfma_i32_16x16x64_i8 v[18:21], v[168:171], v[192:195], v[18:21]
	v_mfma_i32_16x16x64_i8 v[6:9], v[160:163], v[200:203], v[6:9]
	v_mfma_i32_16x16x64_i8 v[2:5], v[168:171], v[200:203], v[2:5]
	s_barrier
	s_setprio 0
	s_andn2_b64 vcc, exec, s[16:17]
	s_mov_b64 s[18:19], -1
	s_mov_b64 s[16:17], 0
	s_movk_i32 s24, 0x100
	s_cbranch_vccz .LBB0_2243
	s_cmpk_lt_u32 s34, 0x100
	s_cbranch_scc0 .LBB0_2246
	s_barrier

; #define PG8_STAGE(bufoff, gbase, voff) do { _Pragma("unroll") for (int _i = 0; _i < 2; ++_i) \
;         __builtin_amdgcn_global_load_lds((const unsigned*)((const char*)(gbase) + (voff)[_i]), (LAS unsigned*)(lds + (bufoff) + ldsw + _i * 8192), 16, 0, 0); } while (0)
; #define PG8_LDA(dst, b, h) do { _Pragma("unroll") for (int m = 0; m < 4; ++m) _Pragma("unroll") for (int k = 0; k < 2; ++k) dst[m][k] = *(const LAS bf16x8*)(lds + PG8_SA(b, h) + aoff + m * 2048 + k * 1024); } while (0)
; #define PG8_LDB(dst, b, h) do { _Pragma("unroll") for (int n = 0; n < 2; ++n) _Pragma("unroll") for (int k = 0; k < 2; ++k) dst[n][k] = *(const LAS bf16x8*)(lds + PG8_SB(b, h) + boff + n * 2048 + k * 1024); } while (0)
; #define PG8_WAIT_V(n) asm volatile("s_waitcnt vmcnt(" #n ")" ::: "memory")
; #define PG8_WAIT_L(n) asm volatile("s_waitcnt lgkmcnt(" #n ")" ::: "memory")
; #define PG8_BAR __builtin_amdgcn_s_barrier()
; #define PG8_SCHED __builtin_amdgcn_sched_barrier(0)
; template <class Epi, class Geom, class Sched, bool ALIGN_EPI, bool I8 = false>
; __device__ __forceinline__ void gemm_phase(LAS unsigned char* lds, const Gemm g, const Sched& S, const Epi& E) {
;     ...
;         for (int t = 0; t < nt; t += 2) {
;             const bool last = (t == nt - 2);
;             const char* a1 = cA + (size_t)(t + 1) * kstep;
;             const char* a2 = last ? nA : cA + (size_t)(t + 2) * kstep; const char* b2 = last ? nB : cB + (size_t)(t + 2) * kstep;
;             const char* a3 = a2 + kstep; const char* b3 = b2 + kstep;
;             PG8_LDB(B0, 0, 0); PG8_LDB(B1, 0, 1); PG8_SCHED; PG8_LDA(At, 0, 0); PG8_STAGE(PG8_SA(1, 1), a1 + hsA, voffA);
;             PG8_WAIT_V(8); PG8_WAIT_L(0); PG8_BAR; PG8_MMA(0, 0, At, B0); PG8_MMA(0, 1, At, B1); PG8_BAR; PG8_SCHED;
;             PG8_LDA(At, 0, 1); PG8_STAGE(PG8_SB(0, 0), b2, voffB); PG8_STAGE(PG8_SB(0, 1), b2 + hsB, voffB); PG8_STAGE(PG8_SA(0, 0), a2, voffA);
;             PG8_WAIT_V(8); PG8_WAIT_L(0); PG8_BAR; PG8_MMA(1, 0, At, B0); PG8_MMA(1, 1, At, B1); PG8_BAR; PG8_SCHED;
.LBB0_2520:
	ds_read_b128 v[130:133], v248
	ds_read_b128 v[134:137], v248 offset:1024
	ds_read_b128 v[138:141], v248 offset:2048
	ds_read_b128 v[142:145], v248 offset:3072
	ds_read_b128 v[146:149], v249
	ds_read_b128 v[150:153], v249 offset:1024
	ds_read_b128 v[154:157], v249 offset:2048
	ds_read_b128 v[158:161], v249 offset:3072
	s_add_u32 s62, s20, 0xfff80080
	s_addc_u32 s63, s21, -1
	s_cmp_eq_u32 s69, 28
	s_cselect_b32 s67, s3, s63
	s_cselect_b32 s66, s33, s62
	s_cselect_b32 s63, s55, s68
	s_cselect_b32 s62, s57, s65
	v_lshl_add_u64 v[166:167], s[20:21], 0, v[182:183]
	s_add_i32 m0, s78, 0xc000
	ds_read_b128 v[162:165], v250
	ds_read_b128 v[190:193], v250 offset:1024
	ds_read_b128 v[194:197], v250 offset:2048
	ds_read_b128 v[198:201], v250 offset:3072
	ds_read_b128 v[202:205], v250 offset:4096
	ds_read_b128 v[206:209], v250 offset:5120
	ds_read_b128 v[210:213], v250 offset:6144
	ds_read_b128 v[214:217], v250 offset:7168
	global_load_lds_dwordx4 v[166:167], off
	v_lshl_add_u64 v[166:167], s[20:21], 0, v[184:185]
	s_add_i32 m0, s78, 0xe000
	s_nop 0
	global_load_lds_dwordx4 v[166:167], off
	s_waitcnt vmcnt(8)
	s_waitcnt lgkmcnt(0)
	s_setprio 1
	s_barrier
	s_waitcnt lgkmcnt(0)
	v_mfma_i32_16x16x64_i8 v[126:129], v[130:133], v[162:165], v[126:129]
	v_mfma_i32_16x16x64_i8 v[122:125], v[138:141], v[162:165], v[122:125]
	v_mfma_i32_16x16x64_i8 v[114:117], v[130:133], v[194:197], v[114:117]
	v_mfma_i32_16x16x64_i8 v[106:109], v[138:141], v[194:197], v[106:109]
	v_mfma_i32_16x16x64_i8 v[102:105], v[130:133], v[202:205], v[102:105]
	v_mfma_i32_16x16x64_i8 v[94:97], v[138:141], v[202:205], v[94:97]
	v_mfma_i32_16x16x64_i8 v[86:89], v[130:133], v[210:213], v[86:89]
	v_mfma_i32_16x16x64_i8 v[78:81], v[138:141], v[210:213], v[78:81]
	v_mfma_i32_16x16x64_i8 v[126:129], v[134:137], v[190:193], v[126:129]
	v_mfma_i32_16x16x64_i8 v[122:125], v[142:145], v[190:193], v[122:125]
	v_mfma_i32_16x16x64_i8 v[114:117], v[134:137], v[198:201], v[114:117]
	v_mfma_i32_16x16x64_i8 v[106:109], v[142:145], v[198:201], v[106:109]
	v_mfma_i32_16x16x64_i8 v[102:105], v[134:137], v[206:209], v[102:105]
	v_mfma_i32_16x16x64_i8 v[94:97], v[142:145], v[206:209], v[94:97]
	v_mfma_i32_16x16x64_i8 v[86:89], v[134:137], v[214:217], v[86:89]
	v_mfma_i32_16x16x64_i8 v[78:81], v[142:145], v[214:217], v[78:81]
	v_mfma_i32_16x16x64_i8 v[118:121], v[146:149], v[162:165], v[118:121]
	v_mfma_i32_16x16x64_i8 v[82:85], v[154:157], v[162:165], v[82:85]
	v_mfma_i32_16x16x64_i8 v[110:113], v[146:149], v[194:197], v[110:113]
	v_mfma_i32_16x16x64_i8 v[74:77], v[154:157], v[194:197], v[74:77]
	v_mfma_i32_16x16x64_i8 v[98:101], v[146:149], v[202:205], v[98:101]
	v_mfma_i32_16x16x64_i8 v[66:69], v[154:157], v[202:205], v[66:69]
	v_mfma_i32_16x16x64_i8 v[90:93], v[146:149], v[210:213], v[90:93]
	v_mfma_i32_16x16x64_i8 v[58:61], v[154:157], v[210:213], v[58:61]
	v_mfma_i32_16x16x64_i8 v[118:121], v[150:153], v[190:193], v[118:121]
	v_mfma_i32_16x16x64_i8 v[82:85], v[158:161], v[190:193], v[82:85]
	v_mfma_i32_16x16x64_i8 v[110:113], v[150:153], v[198:201], v[110:113]
	v_mfma_i32_16x16x64_i8 v[74:77], v[158:161], v[198:201], v[74:77]
	v_mfma_i32_16x16x64_i8 v[98:101], v[150:153], v[206:209], v[98:101]
	v_mfma_i32_16x16x64_i8 v[66:69], v[158:161], v[206:209], v[66:69]
	v_mfma_i32_16x16x64_i8 v[90:93], v[150:153], v[214:217], v[90:93]
	v_mfma_i32_16x16x64_i8 v[58:61], v[158:161], v[214:217], v[58:61]
	s_barrier
	s_setprio 0
	s_add_i32 s70, s92, s77
	v_lshl_add_u64 v[166:167], s[62:63], 0, v[170:171]
	s_mov_b32 m0, s70
	ds_read_b128 v[162:165], v250 offset:16384
	ds_read_b128 v[190:193], v250 offset:17408
	ds_read_b128 v[194:197], v250 offset:18432
	ds_read_b128 v[198:201], v250 offset:19456
	ds_read_b128 v[202:205], v250 offset:20480
	ds_read_b128 v[206:209], v250 offset:21504
	ds_read_b128 v[210:213], v250 offset:22528
	ds_read_b128 v[214:217], v250 offset:23552
	global_load_lds_dwordx4 v[166:167], off
	s_add_i32 m0, s70, 0x2000
	s_add_u32 s70, s62, 0x80000
	v_lshl_add_u64 v[218:219], s[62:63], 0, v[174:175]
	s_addc_u32 s71, s63, 0
	s_add_i32 s72, s93, s77
	global_load_lds_dwordx4 v[218:219], off
	v_lshl_add_u64 v[220:221], s[70:71], 0, v[170:171]
	s_mov_b32 m0, s72
	v_lshl_add_u64 v[222:223], s[66:67], 0, v[172:173]
	global_load_lds_dwordx4 v[220:221], off
	v_lshl_add_u64 v[220:221], s[70:71], 0, v[174:175]
	s_add_i32 m0, s72, 0x2000
	s_nop 0
	global_load_lds_dwordx4 v[220:221], off
	v_lshl_add_u64 v[220:221], s[66:67], 0, v[168:169]
	s_mov_b32 m0, s78
	s_nop 0
	global_load_lds_dwordx4 v[220:221], off
	s_mov_b32 m0, s79
	s_nop 0
	global_load_lds_dwordx4 v[222:223], off
	s_waitcnt vmcnt(8)
	s_waitcnt lgkmcnt(0)
	s_setprio 1
	s_barrier
; #define PG8_STAGE(bufoff, gbase, voff) do { _Pragma("unroll") for (int _i = 0; _i < 2; ++_i) \
;         __builtin_amdgcn_global_load_lds((const unsigned*)((const char*)(gbase) + (voff)[_i]), (LAS unsigned*)(lds + (bufoff) + ldsw + _i * 8192), 16, 0, 0); } while (0)
; #define PG8_LDA(dst, b, h) do { _Pragma("unroll") for (int m = 0; m < 4; ++m) _Pragma("unroll") for (int k = 0; k < 2; ++k) dst[m][k] = *(const LAS bf16x8*)(lds + PG8_SA(b, h) + aoff + m * 2048 + k * 1024); } while (0)
; #define PG8_LDB(dst, b, h) do { _Pragma("unroll") for (int n = 0; n < 2; ++n) _Pragma("unroll") for (int k = 0; k < 2; ++k) dst[n][k] = *(const LAS bf16x8*)(lds + PG8_SB(b, h) + boff + n * 2048 + k * 1024); } while (0)
; #define PG8_WAIT_V(n) asm volatile("s_waitcnt vmcnt(" #n ")" ::: "memory")
; #define PG8_WAIT_L(n) asm volatile("s_waitcnt lgkmcnt(" #n ")" ::: "memory")
; #define PG8_BAR __builtin_amdgcn_s_barrier()
; #define PG8_SCHED __builtin_amdgcn_sched_barrier(0)
; template <class Epi, class Geom, class Sched, bool ALIGN_EPI, bool I8 = false>
; __device__ __forceinline__ void gemm_phase(LAS unsigned char* lds, const Gemm g, const Sched& S, const Epi& E) {
;     ...
;             PG8_WAIT_V(8); PG8_WAIT_L(0); PG8_BAR; PG8_MMA(1, 0, At, B0); PG8_MMA(1, 1, At, B1); PG8_BAR; PG8_SCHED;
;             PG8_LDB(B0, 1, 0); PG8_LDB(B1, 1, 1); PG8_SCHED; PG8_LDA(At, 1, 0); PG8_STAGE(PG8_SA(0, 1), a2 + hsA, voffA);
;             PG8_WAIT_V(8); PG8_WAIT_L(0); PG8_BAR; PG8_MMA(0, 0, At, B0); PG8_MMA(0, 1, At, B1); PG8_BAR; PG8_SCHED;
	s_waitcnt lgkmcnt(0)
	v_mfma_i32_16x16x64_i8 v[70:73], v[130:133], v[162:165], v[70:73]
	v_mfma_i32_16x16x64_i8 v[62:65], v[138:141], v[162:165], v[62:65]
	v_mfma_i32_16x16x64_i8 v[38:41], v[130:133], v[194:197], v[38:41]
	v_mfma_i32_16x16x64_i8 v[54:57], v[138:141], v[194:197], v[54:57]
	v_mfma_i32_16x16x64_i8 v[30:33], v[130:133], v[202:205], v[30:33]
	v_mfma_i32_16x16x64_i8 v[50:53], v[138:141], v[202:205], v[50:53]
	v_mfma_i32_16x16x64_i8 v[26:29], v[130:133], v[210:213], v[26:29]
	v_mfma_i32_16x16x64_i8 v[18:21], v[138:141], v[210:213], v[18:21]
	v_mfma_i32_16x16x64_i8 v[70:73], v[134:137], v[190:193], v[70:73]
	v_mfma_i32_16x16x64_i8 v[62:65], v[142:145], v[190:193], v[62:65]
	v_mfma_i32_16x16x64_i8 v[38:41], v[134:137], v[198:201], v[38:41]
	v_mfma_i32_16x16x64_i8 v[54:57], v[142:145], v[198:201], v[54:57]
	v_mfma_i32_16x16x64_i8 v[30:33], v[134:137], v[206:209], v[30:33]
	v_mfma_i32_16x16x64_i8 v[50:53], v[142:145], v[206:209], v[50:53]
	v_mfma_i32_16x16x64_i8 v[26:29], v[134:137], v[214:217], v[26:29]
	v_mfma_i32_16x16x64_i8 v[18:21], v[142:145], v[214:217], v[18:21]
	v_mfma_i32_16x16x64_i8 v[46:49], v[146:149], v[162:165], v[46:49]
	v_mfma_i32_16x16x64_i8 v[14:17], v[154:157], v[162:165], v[14:17]
	v_mfma_i32_16x16x64_i8 v[42:45], v[146:149], v[194:197], v[42:45]
	v_mfma_i32_16x16x64_i8 v[10:13], v[154:157], v[194:197], v[10:13]
	v_mfma_i32_16x16x64_i8 v[34:37], v[146:149], v[202:205], v[34:37]
	v_mfma_i32_16x16x64_i8 v[6:9], v[154:157], v[202:205], v[6:9]
	v_mfma_i32_16x16x64_i8 v[22:25], v[146:149], v[210:213], v[22:25]
	v_mfma_i32_16x16x64_i8 v[2:5], v[154:157], v[210:213], v[2:5]
	v_mfma_i32_16x16x64_i8 v[46:49], v[150:153], v[190:193], v[46:49]
	v_mfma_i32_16x16x64_i8 v[14:17], v[158:161], v[190:193], v[14:17]
	v_mfma_i32_16x16x64_i8 v[42:45], v[150:153], v[198:201], v[42:45]
	v_mfma_i32_16x16x64_i8 v[10:13], v[158:161], v[198:201], v[10:13]
	v_mfma_i32_16x16x64_i8 v[34:37], v[150:153], v[206:209], v[34:37]
	v_mfma_i32_16x16x64_i8 v[6:9], v[158:161], v[206:209], v[6:9]
	v_mfma_i32_16x16x64_i8 v[22:25], v[150:153], v[214:217], v[22:25]
	v_mfma_i32_16x16x64_i8 v[2:5], v[158:161], v[214:217], v[2:5]
	s_barrier
	s_setprio 0
	s_add_i32 s70, 0, 0x18000
	s_add_i32 s71, 0, 0x1c000
	v_add_u32_e32 v142, s70, v1
	v_add_u32_e32 v158, s71, v1
	ds_read_b128 v[130:133], v142
	ds_read_b128 v[134:137], v142 offset:1024
	ds_read_b128 v[138:141], v142 offset:2048
	ds_read_b128 v[142:145], v142 offset:3072
	ds_read_b128 v[146:149], v158
	ds_read_b128 v[150:153], v158 offset:1024
	ds_read_b128 v[154:157], v158 offset:2048
	ds_read_b128 v[158:161], v158 offset:3072
	s_add_u32 s66, s66, 0x80000
	s_addc_u32 s67, s67, 0
	s_mov_b32 m0, s80
	v_lshl_add_u64 v[224:225], s[66:67], 0, v[168:169]
	ds_read_b128 v[162:165], v250 offset:32768
	ds_read_b128 v[190:193], v250 offset:33792
	ds_read_b128 v[194:197], v250 offset:34816
	ds_read_b128 v[198:201], v250 offset:35840
	ds_read_b128 v[202:205], v250 offset:36864
	ds_read_b128 v[206:209], v250 offset:37888
	ds_read_b128 v[210:213], v250 offset:38912
	ds_read_b128 v[214:217], v250 offset:39936
	global_load_lds_dwordx4 v[224:225], off
	v_lshl_add_u64 v[224:225], s[66:67], 0, v[172:173]
	s_mov_b32 m0, s81
	s_nop 0
	global_load_lds_dwordx4 v[224:225], off
	s_waitcnt vmcnt(8)
	s_waitcnt lgkmcnt(0)
	s_setprio 1
	s_barrier
	s_waitcnt lgkmcnt(0)
	v_mfma_i32_16x16x64_i8 v[126:129], v[130:133], v[162:165], v[126:129]
	v_mfma_i32_16x16x64_i8 v[122:125], v[138:141], v[162:165], v[122:125]
	v_mfma_i32_16x16x64_i8 v[114:117], v[130:133], v[194:197], v[114:117]
	v_mfma_i32_16x16x64_i8 v[106:109], v[138:141], v[194:197], v[106:109]
	v_mfma_i32_16x16x64_i8 v[102:105], v[130:133], v[202:205], v[102:105]
	v_mfma_i32_16x16x64_i8 v[94:97], v[138:141], v[202:205], v[94:97]
	v_mfma_i32_16x16x64_i8 v[86:89], v[130:133], v[210:213], v[86:89]
	v_mfma_i32_16x16x64_i8 v[78:81], v[138:141], v[210:213], v[78:81]
	v_mfma_i32_16x16x64_i8 v[126:129], v[134:137], v[190:193], v[126:129]
	v_mfma_i32_16x16x64_i8 v[122:125], v[142:145], v[190:193], v[122:125]
	v_mfma_i32_16x16x64_i8 v[114:117], v[134:137], v[198:201], v[114:117]
	v_mfma_i32_16x16x64_i8 v[106:109], v[142:145], v[198:201], v[106:109]
	v_mfma_i32_16x16x64_i8 v[102:105], v[134:137], v[206:209], v[102:105]
	v_mfma_i32_16x16x64_i8 v[94:97], v[142:145], v[206:209], v[94:97]
	v_mfma_i32_16x16x64_i8 v[86:89], v[134:137], v[214:217], v[86:89]
	v_mfma_i32_16x16x64_i8 v[78:81], v[142:145], v[214:217], v[78:81]
	v_mfma_i32_16x16x64_i8 v[118:121], v[146:149], v[162:165], v[118:121]
	v_mfma_i32_16x16x64_i8 v[82:85], v[154:157], v[162:165], v[82:85]
	v_mfma_i32_16x16x64_i8 v[110:113], v[146:149], v[194:197], v[110:113]
	v_mfma_i32_16x16x64_i8 v[74:77], v[154:157], v[194:197], v[74:77]
	v_mfma_i32_16x16x64_i8 v[98:101], v[146:149], v[202:205], v[98:101]
	v_mfma_i32_16x16x64_i8 v[66:69], v[154:157], v[202:205], v[66:69]
	v_mfma_i32_16x16x64_i8 v[90:93], v[146:149], v[210:213], v[90:93]
	v_mfma_i32_16x16x64_i8 v[58:61], v[154:157], v[210:213], v[58:61]
	v_mfma_i32_16x16x64_i8 v[118:121], v[150:153], v[190:193], v[118:121]
	v_mfma_i32_16x16x64_i8 v[82:85], v[158:161], v[190:193], v[82:85]
	v_mfma_i32_16x16x64_i8 v[110:113], v[150:153], v[198:201], v[110:113]
	v_mfma_i32_16x16x64_i8 v[74:77], v[158:161], v[198:201], v[74:77]
	v_mfma_i32_16x16x64_i8 v[98:101], v[150:153], v[206:209], v[98:101]
	v_mfma_i32_16x16x64_i8 v[66:69], v[158:161], v[206:209], v[66:69]
	v_mfma_i32_16x16x64_i8 v[90:93], v[150:153], v[214:217], v[90:93]
	v_mfma_i32_16x16x64_i8 v[58:61], v[158:161], v[214:217], v[58:61]
	s_barrier
; #define PG8_STAGE(bufoff, gbase, voff) do { _Pragma("unroll") for (int _i = 0; _i < 2; ++_i) \
;         __builtin_amdgcn_global_load_lds((const unsigned*)((const char*)(gbase) + (voff)[_i]), (LAS unsigned*)(lds + (bufoff) + ldsw + _i * 8192), 16, 0, 0); } while (0)
; #define PG8_LDA(dst, b, h) do { _Pragma("unroll") for (int m = 0; m < 4; ++m) _Pragma("unroll") for (int k = 0; k < 2; ++k) dst[m][k] = *(const LAS bf16x8*)(lds + PG8_SA(b, h) + aoff + m * 2048 + k * 1024); } while (0)
; #define PG8_WAIT_V(n) asm volatile("s_waitcnt vmcnt(" #n ")" ::: "memory")
; #define PG8_WAIT_L(n) asm volatile("s_waitcnt lgkmcnt(" #n ")" ::: "memory")
; #define PG8_BAR __builtin_amdgcn_s_barrier()
; #define PG8_SCHED __builtin_amdgcn_sched_barrier(0)
; template <class Epi, class Geom, class Sched, bool ALIGN_EPI, bool I8 = false>
; __device__ __forceinline__ void gemm_phase(LAS unsigned char* lds, const Gemm g, const Sched& S, const Epi& E) {
;     ...
;             PG8_LDA(At, 1, 1); PG8_STAGE(PG8_SB(1, 0), b3, voffB); PG8_STAGE(PG8_SB(1, 1), b3 + hsB, voffB); PG8_STAGE(PG8_SA(1, 0), a3, voffA);
;             PG8_WAIT_V(8); PG8_WAIT_L(0); PG8_BAR; PG8_MMA(1, 0, At, B0); PG8_MMA(1, 1, At, B1); PG8_BAR; PG8_SCHED;
;         }
	s_setprio 0
	s_add_i32 s66, s70, s77
	v_lshl_add_u64 v[166:167], v[166:167], 0, s[28:29]
	s_mov_b32 m0, s66
	ds_read_b128 v[162:165], v250 offset:49152
	ds_read_b128 v[190:193], v250 offset:50176
	ds_read_b128 v[194:197], v250 offset:51200
	ds_read_b128 v[198:201], v250 offset:52224
	ds_read_b128 v[202:205], v250 offset:53248
	ds_read_b128 v[206:209], v250 offset:54272
	ds_read_b128 v[210:213], v250 offset:55296
	ds_read_b128 v[214:217], v250 offset:56320
	global_load_lds_dwordx4 v[166:167], off
	s_add_i32 m0, s66, 0x2000
	s_add_u32 s62, s62, 0x80080
	v_lshl_add_u64 v[166:167], v[218:219], 0, s[28:29]
	s_addc_u32 s63, s63, 0
	s_add_i32 s66, s71, s77
	global_load_lds_dwordx4 v[166:167], off
	v_lshl_add_u64 v[166:167], s[62:63], 0, v[170:171]
	s_mov_b32 m0, s66
	s_nop 0
	global_load_lds_dwordx4 v[166:167], off
	v_lshl_add_u64 v[166:167], s[62:63], 0, v[174:175]
	s_add_i32 m0, s66, 0x2000
	s_nop 0
	global_load_lds_dwordx4 v[166:167], off
	v_lshl_add_u64 v[166:167], v[220:221], 0, s[28:29]
	s_mov_b32 m0, s88
	s_nop 0
	global_load_lds_dwordx4 v[166:167], off
	v_lshl_add_u64 v[166:167], v[222:223], 0, s[28:29]
	s_mov_b32 m0, s89
	s_nop 0
	global_load_lds_dwordx4 v[166:167], off
	s_waitcnt vmcnt(8)
	s_waitcnt lgkmcnt(0)
	s_setprio 1
	s_barrier
	s_waitcnt lgkmcnt(0)
	v_mfma_i32_16x16x64_i8 v[70:73], v[130:133], v[162:165], v[70:73]
	v_mfma_i32_16x16x64_i8 v[62:65], v[138:141], v[162:165], v[62:65]
	v_mfma_i32_16x16x64_i8 v[38:41], v[130:133], v[194:197], v[38:41]
	v_mfma_i32_16x16x64_i8 v[54:57], v[138:141], v[194:197], v[54:57]
	v_mfma_i32_16x16x64_i8 v[30:33], v[130:133], v[202:205], v[30:33]
	v_mfma_i32_16x16x64_i8 v[50:53], v[138:141], v[202:205], v[50:53]
	v_mfma_i32_16x16x64_i8 v[26:29], v[130:133], v[210:213], v[26:29]
	v_mfma_i32_16x16x64_i8 v[18:21], v[138:141], v[210:213], v[18:21]
	v_mfma_i32_16x16x64_i8 v[70:73], v[134:137], v[190:193], v[70:73]
	v_mfma_i32_16x16x64_i8 v[62:65], v[142:145], v[190:193], v[62:65]
	v_mfma_i32_16x16x64_i8 v[38:41], v[134:137], v[198:201], v[38:41]
	v_mfma_i32_16x16x64_i8 v[54:57], v[142:145], v[198:201], v[54:57]
	v_mfma_i32_16x16x64_i8 v[30:33], v[134:137], v[206:209], v[30:33]
	v_mfma_i32_16x16x64_i8 v[50:53], v[142:145], v[206:209], v[50:53]
	v_mfma_i32_16x16x64_i8 v[26:29], v[134:137], v[214:217], v[26:29]
	v_mfma_i32_16x16x64_i8 v[18:21], v[142:145], v[214:217], v[18:21]
	v_mfma_i32_16x16x64_i8 v[46:49], v[146:149], v[162:165], v[46:49]
	v_mfma_i32_16x16x64_i8 v[14:17], v[154:157], v[162:165], v[14:17]
	v_mfma_i32_16x16x64_i8 v[42:45], v[146:149], v[194:197], v[42:45]
	v_mfma_i32_16x16x64_i8 v[10:13], v[154:157], v[194:197], v[10:13]
	v_mfma_i32_16x16x64_i8 v[34:37], v[146:149], v[202:205], v[34:37]
	v_mfma_i32_16x16x64_i8 v[6:9], v[154:157], v[202:205], v[6:9]
	v_mfma_i32_16x16x64_i8 v[22:25], v[146:149], v[210:213], v[22:25]
	v_mfma_i32_16x16x64_i8 v[2:5], v[154:157], v[210:213], v[2:5]
	v_mfma_i32_16x16x64_i8 v[46:49], v[150:153], v[190:193], v[46:49]
	v_mfma_i32_16x16x64_i8 v[14:17], v[158:161], v[190:193], v[14:17]
	v_mfma_i32_16x16x64_i8 v[42:45], v[150:153], v[198:201], v[42:45]
	v_mfma_i32_16x16x64_i8 v[10:13], v[158:161], v[198:201], v[10:13]
	v_mfma_i32_16x16x64_i8 v[34:37], v[150:153], v[206:209], v[34:37]
	v_mfma_i32_16x16x64_i8 v[6:9], v[158:161], v[206:209], v[6:9]
	v_mfma_i32_16x16x64_i8 v[22:25], v[150:153], v[214:217], v[22:25]
	v_mfma_i32_16x16x64_i8 v[2:5], v[158:161], v[214:217], v[2:5]
	s_barrier
	s_setprio 0
	s_add_i32 s69, s69, 2
	s_add_u32 s20, s20, 0x100
	s_addc_u32 s21, s21, 0
	s_add_u32 s65, s65, 0x100
	s_addc_u32 s68, s68, 0
	s_cmp_gt_u32 s69, 29
	s_cbranch_scc0 .LBB0_2520
	s_and_b64 vcc, exec, s[30:31]
	s_cbranch_vccz .LBB0_2523
	s_barrier

; #define PG8_STAGE(bufoff, gbase, voff) do { _Pragma("unroll") for (int _i = 0; _i < 2; ++_i) \
;         __builtin_amdgcn_global_load_lds((const unsigned*)((const char*)(gbase) + (voff)[_i]), (LAS unsigned*)(lds + (bufoff) + ldsw + _i * 8192), 16, 0, 0); } while (0)
; #define PG8_LDA(dst, b, h) do { _Pragma("unroll") for (int m = 0; m < 4; ++m) _Pragma("unroll") for (int k = 0; k < 2; ++k) dst[m][k] = *(const LAS bf16x8*)(lds + PG8_SA(b, h) + aoff + m * 2048 + k * 1024); } while (0)
; #define PG8_LDB(dst, b, h) do { _Pragma("unroll") for (int n = 0; n < 2; ++n) _Pragma("unroll") for (int k = 0; k < 2; ++k) dst[n][k] = *(const LAS bf16x8*)(lds + PG8_SB(b, h) + boff + n * 2048 + k * 1024); } while (0)
; #define PG8_WAIT_V(n) asm volatile("s_waitcnt vmcnt(" #n ")" ::: "memory")
; #define PG8_WAIT_L(n) asm volatile("s_waitcnt lgkmcnt(" #n ")" ::: "memory")
; #define PG8_BAR __builtin_amdgcn_s_barrier()
; #define PG8_SCHED __builtin_amdgcn_sched_barrier(0)
; template <class Epi, class Geom, class Sched, bool ALIGN_EPI, bool I8 = false>
; __device__ __forceinline__ void gemm_phase(LAS unsigned char* lds, const Gemm g, const Sched& S, const Epi& E) {
;     ...
;         for (int t = 0; t < nt; t += 2) {
;             const bool last = (t == nt - 2);
;             const char* a1 = cA + (size_t)(t + 1) * kstep;
;             const char* a2 = last ? nA : cA + (size_t)(t + 2) * kstep; const char* b2 = last ? nB : cB + (size_t)(t + 2) * kstep;
;             const char* a3 = a2 + kstep; const char* b3 = b2 + kstep;
;             PG8_LDB(B0, 0, 0); PG8_LDB(B1, 0, 1); PG8_SCHED; PG8_LDA(At, 0, 0); PG8_STAGE(PG8_SA(1, 1), a1 + hsA, voffA);
;             PG8_WAIT_V(8); PG8_WAIT_L(0); PG8_BAR; PG8_MMA(0, 0, At, B0); PG8_MMA(0, 1, At, B1); PG8_BAR; PG8_SCHED;
;             PG8_LDA(At, 0, 1); PG8_STAGE(PG8_SB(0, 0), b2, voffB); PG8_STAGE(PG8_SB(0, 1), b2 + hsB, voffB); PG8_STAGE(PG8_SA(0, 0), a2, voffA);
;             PG8_WAIT_V(8); PG8_WAIT_L(0); PG8_BAR; PG8_MMA(1, 0, At, B0); PG8_MMA(1, 1, At, B1); PG8_BAR; PG8_SCHED;
.LBB0_2872:
	ds_read_b128 v[90:93], v181
	ds_read_b128 v[98:101], v181 offset:1024
	ds_read_b128 v[102:105], v181 offset:2048
	ds_read_b128 v[160:163], v181 offset:3072
	ds_read_b128 v[182:185], v206
	ds_read_b128 v[186:189], v206 offset:1024
	ds_read_b128 v[190:193], v206 offset:2048
	ds_read_b128 v[194:197], v206 offset:3072
	s_add_u32 s38, s36, 0xffe80080
	s_addc_u32 s39, s37, -1
	s_cmpk_eq_i32 s62, 0x5c
	s_cselect_b32 s41, s1, s39
	s_cselect_b32 s40, s0, s38
	s_cselect_b32 s39, s35, s61
	s_cselect_b32 s38, s34, s60
	v_lshl_add_u64 v[152:153], s[36:37], 0, v[146:147]
	s_add_i32 m0, s33, 0xc000
	ds_read_b128 v[198:201], v207
	ds_read_b128 v[202:205], v207 offset:1024
	ds_read_b128 v[208:211], v207 offset:2048
	ds_read_b128 v[212:215], v207 offset:3072
	ds_read_b128 v[216:219], v207 offset:4096
	ds_read_b128 v[220:223], v207 offset:5120
	ds_read_b128 v[224:227], v207 offset:6144
	ds_read_b128 v[228:231], v207 offset:7168
	global_load_lds_dwordx4 v[152:153], off
	v_lshl_add_u64 v[152:153], s[36:37], 0, v[148:149]
	s_add_i32 m0, s33, 0xe000
	s_nop 0
	global_load_lds_dwordx4 v[152:153], off
	s_waitcnt vmcnt(8)
	s_waitcnt lgkmcnt(0)
	s_setprio 1
	s_barrier
	s_waitcnt lgkmcnt(0)
	v_mfma_i32_16x16x64_i8 v[94:97], v[90:93], v[198:201], v[94:97]
	v_mfma_i32_16x16x64_i8 v[138:141], v[102:105], v[198:201], v[138:141]
	v_mfma_i32_16x16x64_i8 v[130:133], v[90:93], v[208:211], v[130:133]
	v_mfma_i32_16x16x64_i8 v[122:125], v[102:105], v[208:211], v[122:125]
	v_mfma_i32_16x16x64_i8 v[110:113], v[90:93], v[216:219], v[110:113]
	v_mfma_i32_16x16x64_i8 v[106:109], v[102:105], v[216:219], v[106:109]
	v_mfma_i32_16x16x64_i8 v[82:85], v[90:93], v[224:227], v[82:85]
	v_mfma_i32_16x16x64_i8 v[74:77], v[102:105], v[224:227], v[74:77]
	v_mfma_i32_16x16x64_i8 v[94:97], v[98:101], v[202:205], v[94:97]
	v_mfma_i32_16x16x64_i8 v[138:141], v[160:163], v[202:205], v[138:141]
	v_mfma_i32_16x16x64_i8 v[130:133], v[98:101], v[212:215], v[130:133]
	v_mfma_i32_16x16x64_i8 v[122:125], v[160:163], v[212:215], v[122:125]
	v_mfma_i32_16x16x64_i8 v[110:113], v[98:101], v[220:223], v[110:113]
	v_mfma_i32_16x16x64_i8 v[106:109], v[160:163], v[220:223], v[106:109]
	v_mfma_i32_16x16x64_i8 v[82:85], v[98:101], v[228:231], v[82:85]
	v_mfma_i32_16x16x64_i8 v[74:77], v[160:163], v[228:231], v[74:77]
	v_mfma_i32_16x16x64_i8 v[134:137], v[182:185], v[198:201], v[134:137]
	v_mfma_i32_16x16x64_i8 v[126:129], v[190:193], v[198:201], v[126:129]
	v_mfma_i32_16x16x64_i8 v[118:121], v[182:185], v[208:211], v[118:121]
	v_mfma_i32_16x16x64_i8 v[114:117], v[190:193], v[208:211], v[114:117]
	v_mfma_i32_16x16x64_i8 v[86:89], v[182:185], v[216:219], v[86:89]
	v_mfma_i32_16x16x64_i8 v[78:81], v[190:193], v[216:219], v[78:81]
	v_mfma_i32_16x16x64_i8 v[70:73], v[182:185], v[224:227], v[70:73]
	v_mfma_i32_16x16x64_i8 v[66:69], v[190:193], v[224:227], v[66:69]
	v_mfma_i32_16x16x64_i8 v[134:137], v[186:189], v[202:205], v[134:137]
	v_mfma_i32_16x16x64_i8 v[126:129], v[194:197], v[202:205], v[126:129]
	v_mfma_i32_16x16x64_i8 v[118:121], v[186:189], v[212:215], v[118:121]
	v_mfma_i32_16x16x64_i8 v[114:117], v[194:197], v[212:215], v[114:117]
	v_mfma_i32_16x16x64_i8 v[86:89], v[186:189], v[220:223], v[86:89]
	v_mfma_i32_16x16x64_i8 v[78:81], v[194:197], v[220:223], v[78:81]
	v_mfma_i32_16x16x64_i8 v[70:73], v[186:189], v[228:231], v[70:73]
	v_mfma_i32_16x16x64_i8 v[66:69], v[194:197], v[228:231], v[66:69]
	s_barrier
	s_setprio 0
	s_add_i32 s63, s14, s46
	v_lshl_add_u64 v[152:153], s[38:39], 0, v[144:145]
	s_mov_b32 m0, s63
	ds_read_b128 v[198:201], v207 offset:16384
	ds_read_b128 v[202:205], v207 offset:17408
	ds_read_b128 v[208:211], v207 offset:18432
	ds_read_b128 v[212:215], v207 offset:19456
	ds_read_b128 v[216:219], v207 offset:20480
	ds_read_b128 v[220:223], v207 offset:21504
	ds_read_b128 v[224:227], v207 offset:22528
	ds_read_b128 v[228:231], v207 offset:23552
	global_load_lds_dwordx4 v[152:153], off
	s_add_i32 m0, s63, 0x2000
	s_add_u32 s64, s38, 0x180000
	v_lshl_add_u64 v[156:157], s[38:39], 0, v[142:143]
	s_addc_u32 s65, s39, 0
	s_add_i32 s63, s55, s46
	global_load_lds_dwordx4 v[156:157], off
	v_lshl_add_u64 v[166:167], s[64:65], 0, v[144:145]
	s_mov_b32 m0, s63
	v_lshl_add_u64 v[170:171], s[40:41], 0, v[142:143]
	global_load_lds_dwordx4 v[166:167], off
	v_lshl_add_u64 v[166:167], s[64:65], 0, v[142:143]
	s_add_i32 m0, s63, 0x2000
	s_nop 0
	global_load_lds_dwordx4 v[166:167], off
	v_lshl_add_u64 v[166:167], s[40:41], 0, v[144:145]
	s_mov_b32 m0, s33
	s_nop 0
	global_load_lds_dwordx4 v[166:167], off
	s_mov_b32 m0, s49
	s_nop 0
	global_load_lds_dwordx4 v[170:171], off
	s_waitcnt vmcnt(8)
	s_waitcnt lgkmcnt(0)
	s_setprio 1
	s_barrier
; #define PG8_STAGE(bufoff, gbase, voff) do { _Pragma("unroll") for (int _i = 0; _i < 2; ++_i) \
;         __builtin_amdgcn_global_load_lds((const unsigned*)((const char*)(gbase) + (voff)[_i]), (LAS unsigned*)(lds + (bufoff) + ldsw + _i * 8192), 16, 0, 0); } while (0)
; #define PG8_LDA(dst, b, h) do { _Pragma("unroll") for (int m = 0; m < 4; ++m) _Pragma("unroll") for (int k = 0; k < 2; ++k) dst[m][k] = *(const LAS bf16x8*)(lds + PG8_SA(b, h) + aoff + m * 2048 + k * 1024); } while (0)
; #define PG8_LDB(dst, b, h) do { _Pragma("unroll") for (int n = 0; n < 2; ++n) _Pragma("unroll") for (int k = 0; k < 2; ++k) dst[n][k] = *(const LAS bf16x8*)(lds + PG8_SB(b, h) + boff + n * 2048 + k * 1024); } while (0)
; #define PG8_WAIT_V(n) asm volatile("s_waitcnt vmcnt(" #n ")" ::: "memory")
; #define PG8_WAIT_L(n) asm volatile("s_waitcnt lgkmcnt(" #n ")" ::: "memory")
; #define PG8_BAR __builtin_amdgcn_s_barrier()
; #define PG8_SCHED __builtin_amdgcn_sched_barrier(0)
; template <class Epi, class Geom, class Sched, bool ALIGN_EPI, bool I8 = false>
; __device__ __forceinline__ void gemm_phase(LAS unsigned char* lds, const Gemm g, const Sched& S, const Epi& E) {
;     ...
;             PG8_WAIT_V(8); PG8_WAIT_L(0); PG8_BAR; PG8_MMA(1, 0, At, B0); PG8_MMA(1, 1, At, B1); PG8_BAR; PG8_SCHED;
;             PG8_LDB(B0, 1, 0); PG8_LDB(B1, 1, 1); PG8_SCHED; PG8_LDA(At, 1, 0); PG8_STAGE(PG8_SA(0, 1), a2 + hsA, voffA);
;             PG8_WAIT_V(8); PG8_WAIT_L(0); PG8_BAR; PG8_MMA(0, 0, At, B0); PG8_MMA(0, 1, At, B1); PG8_BAR; PG8_SCHED;
	s_waitcnt lgkmcnt(0)
	v_mfma_i32_16x16x64_i8 v[62:65], v[90:93], v[198:201], v[62:65]
	v_mfma_i32_16x16x64_i8 v[58:61], v[102:105], v[198:201], v[58:61]
	v_mfma_i32_16x16x64_i8 v[50:53], v[90:93], v[208:211], v[50:53]
	v_mfma_i32_16x16x64_i8 v[42:45], v[102:105], v[208:211], v[42:45]
	v_mfma_i32_16x16x64_i8 v[30:33], v[90:93], v[216:219], v[30:33]
	v_mfma_i32_16x16x64_i8 v[26:29], v[102:105], v[216:219], v[26:29]
	v_mfma_i32_16x16x64_i8 v[18:21], v[90:93], v[224:227], v[18:21]
	v_mfma_i32_16x16x64_i8 v[10:13], v[102:105], v[224:227], v[10:13]
	v_mfma_i32_16x16x64_i8 v[62:65], v[98:101], v[202:205], v[62:65]
	v_mfma_i32_16x16x64_i8 v[58:61], v[160:163], v[202:205], v[58:61]
	v_mfma_i32_16x16x64_i8 v[50:53], v[98:101], v[212:215], v[50:53]
	v_mfma_i32_16x16x64_i8 v[42:45], v[160:163], v[212:215], v[42:45]
	v_mfma_i32_16x16x64_i8 v[30:33], v[98:101], v[220:223], v[30:33]
	v_mfma_i32_16x16x64_i8 v[26:29], v[160:163], v[220:223], v[26:29]
	v_mfma_i32_16x16x64_i8 v[18:21], v[98:101], v[228:231], v[18:21]
	v_mfma_i32_16x16x64_i8 v[10:13], v[160:163], v[228:231], v[10:13]
	v_mfma_i32_16x16x64_i8 v[54:57], v[182:185], v[198:201], v[54:57]
	v_mfma_i32_16x16x64_i8 v[46:49], v[190:193], v[198:201], v[46:49]
	v_mfma_i32_16x16x64_i8 v[38:41], v[182:185], v[208:211], v[38:41]
	v_mfma_i32_16x16x64_i8 v[34:37], v[190:193], v[208:211], v[34:37]
	v_mfma_i32_16x16x64_i8 v[22:25], v[182:185], v[216:219], v[22:25]
	v_mfma_i32_16x16x64_i8 v[14:17], v[190:193], v[216:219], v[14:17]
	v_mfma_i32_16x16x64_i8 v[6:9], v[182:185], v[224:227], v[6:9]
	v_mfma_i32_16x16x64_i8 v[2:5], v[190:193], v[224:227], v[2:5]
	v_mfma_i32_16x16x64_i8 v[54:57], v[186:189], v[202:205], v[54:57]
	v_mfma_i32_16x16x64_i8 v[46:49], v[194:197], v[202:205], v[46:49]
	v_mfma_i32_16x16x64_i8 v[38:41], v[186:189], v[212:215], v[38:41]
	v_mfma_i32_16x16x64_i8 v[34:37], v[194:197], v[212:215], v[34:37]
	v_mfma_i32_16x16x64_i8 v[22:25], v[186:189], v[220:223], v[22:25]
	v_mfma_i32_16x16x64_i8 v[14:17], v[194:197], v[220:223], v[14:17]
	v_mfma_i32_16x16x64_i8 v[6:9], v[186:189], v[228:231], v[6:9]
	v_mfma_i32_16x16x64_i8 v[2:5], v[194:197], v[228:231], v[2:5]
	s_barrier
	s_setprio 0
	s_add_i32 s63, 0, 0x18000
	v_add_u32_e32 v154, s63, v175
	s_add_i32 s64, 0, 0x1c000
	ds_read_b128 v[90:93], v154
	ds_read_b128 v[98:101], v154 offset:1024
	ds_read_b128 v[102:105], v154 offset:2048
	ds_read_b128 v[160:163], v154 offset:3072
	v_add_u32_e32 v154, s64, v175
	ds_read_b128 v[182:185], v154
	ds_read_b128 v[186:189], v154 offset:1024
	ds_read_b128 v[190:193], v154 offset:2048
	ds_read_b128 v[194:197], v154 offset:3072
	s_add_u32 s40, s40, 0x180000
	s_addc_u32 s41, s41, 0
	s_mov_b32 m0, s50
	v_lshl_add_u64 v[176:177], s[40:41], 0, v[144:145]
	ds_read_b128 v[198:201], v207 offset:32768
	ds_read_b128 v[202:205], v207 offset:33792
	ds_read_b128 v[208:211], v207 offset:34816
	ds_read_b128 v[212:215], v207 offset:35840
	ds_read_b128 v[216:219], v207 offset:36864
	ds_read_b128 v[220:223], v207 offset:37888
	ds_read_b128 v[224:227], v207 offset:38912
	ds_read_b128 v[228:231], v207 offset:39936
	global_load_lds_dwordx4 v[176:177], off
	v_lshl_add_u64 v[176:177], s[40:41], 0, v[142:143]
	s_mov_b32 m0, s51
	s_nop 0
	global_load_lds_dwordx4 v[176:177], off
	s_waitcnt vmcnt(8)
	s_waitcnt lgkmcnt(0)
	s_setprio 1
	s_barrier
	s_waitcnt lgkmcnt(0)
	v_mfma_i32_16x16x64_i8 v[94:97], v[90:93], v[198:201], v[94:97]
	v_mfma_i32_16x16x64_i8 v[138:141], v[102:105], v[198:201], v[138:141]
	v_mfma_i32_16x16x64_i8 v[130:133], v[90:93], v[208:211], v[130:133]
	v_mfma_i32_16x16x64_i8 v[122:125], v[102:105], v[208:211], v[122:125]
	v_mfma_i32_16x16x64_i8 v[110:113], v[90:93], v[216:219], v[110:113]
	v_mfma_i32_16x16x64_i8 v[106:109], v[102:105], v[216:219], v[106:109]
	v_mfma_i32_16x16x64_i8 v[82:85], v[90:93], v[224:227], v[82:85]
	v_mfma_i32_16x16x64_i8 v[74:77], v[102:105], v[224:227], v[74:77]
	v_mfma_i32_16x16x64_i8 v[94:97], v[98:101], v[202:205], v[94:97]
	v_mfma_i32_16x16x64_i8 v[138:141], v[160:163], v[202:205], v[138:141]
	v_mfma_i32_16x16x64_i8 v[130:133], v[98:101], v[212:215], v[130:133]
	v_mfma_i32_16x16x64_i8 v[122:125], v[160:163], v[212:215], v[122:125]
	v_mfma_i32_16x16x64_i8 v[110:113], v[98:101], v[220:223], v[110:113]
	v_mfma_i32_16x16x64_i8 v[106:109], v[160:163], v[220:223], v[106:109]
	v_mfma_i32_16x16x64_i8 v[82:85], v[98:101], v[228:231], v[82:85]
	v_mfma_i32_16x16x64_i8 v[74:77], v[160:163], v[228:231], v[74:77]
	v_mfma_i32_16x16x64_i8 v[134:137], v[182:185], v[198:201], v[134:137]
	v_mfma_i32_16x16x64_i8 v[126:129], v[190:193], v[198:201], v[126:129]
	v_mfma_i32_16x16x64_i8 v[118:121], v[182:185], v[208:211], v[118:121]
	v_mfma_i32_16x16x64_i8 v[114:117], v[190:193], v[208:211], v[114:117]
	v_mfma_i32_16x16x64_i8 v[86:89], v[182:185], v[216:219], v[86:89]
	v_mfma_i32_16x16x64_i8 v[78:81], v[190:193], v[216:219], v[78:81]
	v_mfma_i32_16x16x64_i8 v[70:73], v[182:185], v[224:227], v[70:73]
	v_mfma_i32_16x16x64_i8 v[66:69], v[190:193], v[224:227], v[66:69]
	v_mfma_i32_16x16x64_i8 v[134:137], v[186:189], v[202:205], v[134:137]
	v_mfma_i32_16x16x64_i8 v[126:129], v[194:197], v[202:205], v[126:129]
	v_mfma_i32_16x16x64_i8 v[118:121], v[186:189], v[212:215], v[118:121]
	v_mfma_i32_16x16x64_i8 v[114:117], v[194:197], v[212:215], v[114:117]
	v_mfma_i32_16x16x64_i8 v[86:89], v[186:189], v[220:223], v[86:89]
	v_mfma_i32_16x16x64_i8 v[78:81], v[194:197], v[220:223], v[78:81]
	v_mfma_i32_16x16x64_i8 v[70:73], v[186:189], v[228:231], v[70:73]
	v_mfma_i32_16x16x64_i8 v[66:69], v[194:197], v[228:231], v[66:69]
	s_barrier
; #define PG8_STAGE(bufoff, gbase, voff) do { _Pragma("unroll") for (int _i = 0; _i < 2; ++_i) \
;         __builtin_amdgcn_global_load_lds((const unsigned*)((const char*)(gbase) + (voff)[_i]), (LAS unsigned*)(lds + (bufoff) + ldsw + _i * 8192), 16, 0, 0); } while (0)
; #define PG8_LDA(dst, b, h) do { _Pragma("unroll") for (int m = 0; m < 4; ++m) _Pragma("unroll") for (int k = 0; k < 2; ++k) dst[m][k] = *(const LAS bf16x8*)(lds + PG8_SA(b, h) + aoff + m * 2048 + k * 1024); } while (0)
; #define PG8_WAIT_V(n) asm volatile("s_waitcnt vmcnt(" #n ")" ::: "memory")
; #define PG8_WAIT_L(n) asm volatile("s_waitcnt lgkmcnt(" #n ")" ::: "memory")
; #define PG8_BAR __builtin_amdgcn_s_barrier()
; #define PG8_SCHED __builtin_amdgcn_sched_barrier(0)
; template <class Epi, class Geom, class Sched, bool ALIGN_EPI, bool I8 = false>
; __device__ __forceinline__ void gemm_phase(LAS unsigned char* lds, const Gemm g, const Sched& S, const Epi& E) {
;     ...
;             PG8_LDA(At, 1, 1); PG8_STAGE(PG8_SB(1, 0), b3, voffB); PG8_STAGE(PG8_SB(1, 1), b3 + hsB, voffB); PG8_STAGE(PG8_SA(1, 0), a3, voffA);
;             PG8_WAIT_V(8); PG8_WAIT_L(0); PG8_BAR; PG8_MMA(1, 0, At, B0); PG8_MMA(1, 1, At, B1); PG8_BAR; PG8_SCHED;
;         }
	s_setprio 0
	s_add_i32 s40, s63, s46
	v_lshl_add_u64 v[152:153], v[152:153], 0, s[20:21]
	s_mov_b32 m0, s40
	ds_read_b128 v[198:201], v207 offset:49152
	ds_read_b128 v[202:205], v207 offset:50176
	ds_read_b128 v[208:211], v207 offset:51200
	ds_read_b128 v[212:215], v207 offset:52224
	ds_read_b128 v[216:219], v207 offset:53248
	ds_read_b128 v[220:223], v207 offset:54272
	ds_read_b128 v[224:227], v207 offset:55296
	ds_read_b128 v[228:231], v207 offset:56320
	global_load_lds_dwordx4 v[152:153], off
	s_add_i32 m0, s40, 0x2000
	s_add_u32 s38, s38, 0x180080
	v_lshl_add_u64 v[152:153], v[156:157], 0, s[20:21]
	s_addc_u32 s39, s39, 0
	s_add_i32 s40, s64, s46
	global_load_lds_dwordx4 v[152:153], off
	v_lshl_add_u64 v[152:153], s[38:39], 0, v[144:145]
	s_mov_b32 m0, s40
	s_nop 0
	global_load_lds_dwordx4 v[152:153], off
	v_lshl_add_u64 v[152:153], s[38:39], 0, v[142:143]
	s_add_i32 m0, s40, 0x2000
	s_nop 0
	global_load_lds_dwordx4 v[152:153], off
	v_lshl_add_u64 v[152:153], v[166:167], 0, s[20:21]
	s_mov_b32 m0, s52
	s_nop 0
	global_load_lds_dwordx4 v[152:153], off
	v_lshl_add_u64 v[152:153], v[170:171], 0, s[20:21]
	s_mov_b32 m0, s53
	s_nop 0
	global_load_lds_dwordx4 v[152:153], off
	s_waitcnt vmcnt(8)
	s_waitcnt lgkmcnt(0)
	s_setprio 1
	s_barrier
	s_waitcnt lgkmcnt(0)
	v_mfma_i32_16x16x64_i8 v[62:65], v[90:93], v[198:201], v[62:65]
	v_mfma_i32_16x16x64_i8 v[58:61], v[102:105], v[198:201], v[58:61]
	v_mfma_i32_16x16x64_i8 v[50:53], v[90:93], v[208:211], v[50:53]
	v_mfma_i32_16x16x64_i8 v[42:45], v[102:105], v[208:211], v[42:45]
	v_mfma_i32_16x16x64_i8 v[30:33], v[90:93], v[216:219], v[30:33]
	v_mfma_i32_16x16x64_i8 v[26:29], v[102:105], v[216:219], v[26:29]
	v_mfma_i32_16x16x64_i8 v[18:21], v[90:93], v[224:227], v[18:21]
	v_mfma_i32_16x16x64_i8 v[10:13], v[102:105], v[224:227], v[10:13]
	v_mfma_i32_16x16x64_i8 v[62:65], v[98:101], v[202:205], v[62:65]
	v_mfma_i32_16x16x64_i8 v[58:61], v[160:163], v[202:205], v[58:61]
	v_mfma_i32_16x16x64_i8 v[50:53], v[98:101], v[212:215], v[50:53]
	v_mfma_i32_16x16x64_i8 v[42:45], v[160:163], v[212:215], v[42:45]
	v_mfma_i32_16x16x64_i8 v[30:33], v[98:101], v[220:223], v[30:33]
	v_mfma_i32_16x16x64_i8 v[26:29], v[160:163], v[220:223], v[26:29]
	v_mfma_i32_16x16x64_i8 v[18:21], v[98:101], v[228:231], v[18:21]
	v_mfma_i32_16x16x64_i8 v[10:13], v[160:163], v[228:231], v[10:13]
	v_mfma_i32_16x16x64_i8 v[54:57], v[182:185], v[198:201], v[54:57]
	v_mfma_i32_16x16x64_i8 v[46:49], v[190:193], v[198:201], v[46:49]
	v_mfma_i32_16x16x64_i8 v[38:41], v[182:185], v[208:211], v[38:41]
	v_mfma_i32_16x16x64_i8 v[34:37], v[190:193], v[208:211], v[34:37]
	v_mfma_i32_16x16x64_i8 v[22:25], v[182:185], v[216:219], v[22:25]
	v_mfma_i32_16x16x64_i8 v[14:17], v[190:193], v[216:219], v[14:17]
	v_mfma_i32_16x16x64_i8 v[6:9], v[182:185], v[224:227], v[6:9]
	v_mfma_i32_16x16x64_i8 v[2:5], v[190:193], v[224:227], v[2:5]
	v_mfma_i32_16x16x64_i8 v[54:57], v[186:189], v[202:205], v[54:57]
	v_mfma_i32_16x16x64_i8 v[46:49], v[194:197], v[202:205], v[46:49]
	v_mfma_i32_16x16x64_i8 v[38:41], v[186:189], v[212:215], v[38:41]
	v_mfma_i32_16x16x64_i8 v[34:37], v[194:197], v[212:215], v[34:37]
	v_mfma_i32_16x16x64_i8 v[22:25], v[186:189], v[220:223], v[22:25]
	v_mfma_i32_16x16x64_i8 v[14:17], v[194:197], v[220:223], v[14:17]
	v_mfma_i32_16x16x64_i8 v[6:9], v[186:189], v[228:231], v[6:9]
	v_mfma_i32_16x16x64_i8 v[2:5], v[194:197], v[228:231], v[2:5]
	s_barrier
	s_setprio 0
	s_add_i32 s62, s62, 2
	s_add_u32 s36, s36, 0x100
	s_addc_u32 s37, s37, 0
	s_add_u32 s60, s60, 0x100
	s_addc_u32 s61, s61, 0
	s_cmpk_gt_u32 s62, 0x5d
	s_cbranch_scc0 .LBB0_2872
	s_and_b64 vcc, exec, s[22:23]
	s_cbranch_vccz .LBB0_2875
	s_barrier

; #define PG8_STAGE(bufoff, gbase, voff) do { _Pragma("unroll") for (int _i = 0; _i < 2; ++_i) \
;         __builtin_amdgcn_global_load_lds((const unsigned*)((const char*)(gbase) + (voff)[_i]), (LAS unsigned*)(lds + (bufoff) + ldsw + _i * 8192), 16, 0, 0); } while (0)
; #define PG8_LDA(dst, b, h) do { _Pragma("unroll") for (int m = 0; m < 4; ++m) _Pragma("unroll") for (int k = 0; k < 2; ++k) dst[m][k] = *(const LAS bf16x8*)(lds + PG8_SA(b, h) + aoff + m * 2048 + k * 1024); } while (0)
; #define PG8_LDB(dst, b, h) do { _Pragma("unroll") for (int n = 0; n < 2; ++n) _Pragma("unroll") for (int k = 0; k < 2; ++k) dst[n][k] = *(const LAS bf16x8*)(lds + PG8_SB(b, h) + boff + n * 2048 + k * 1024); } while (0)
; #define PG8_WAIT_V(n) asm volatile("s_waitcnt vmcnt(" #n ")" ::: "memory")
; #define PG8_WAIT_L(n) asm volatile("s_waitcnt lgkmcnt(" #n ")" ::: "memory")
; #define PG8_BAR __builtin_amdgcn_s_barrier()
; #define PG8_SCHED __builtin_amdgcn_sched_barrier(0)
; template <class Epi, class Geom, class Sched, bool ALIGN_EPI, bool I8 = false>
; __device__ __forceinline__ void gemm_phase(LAS unsigned char* lds, const Gemm g, const Sched& S, const Epi& E) {
;     ...
;         for (int t = 0; t < nt; t += 2) {
;             const bool last = (t == nt - 2);
;             const char* a1 = cA + (size_t)(t + 1) * kstep;
;             const char* a2 = last ? nA : cA + (size_t)(t + 2) * kstep; const char* b2 = last ? nB : cB + (size_t)(t + 2) * kstep;
;             const char* a3 = a2 + kstep; const char* b3 = b2 + kstep;
;             PG8_LDB(B0, 0, 0); PG8_LDB(B1, 0, 1); PG8_SCHED; PG8_LDA(At, 0, 0); PG8_STAGE(PG8_SA(1, 1), a1 + hsA, voffA);
;             PG8_WAIT_V(8); PG8_WAIT_L(0); PG8_BAR; PG8_MMA(0, 0, At, B0); PG8_MMA(0, 1, At, B1); PG8_BAR; PG8_SCHED;
;             PG8_LDA(At, 0, 1); PG8_STAGE(PG8_SB(0, 0), b2, voffB); PG8_STAGE(PG8_SB(0, 1), b2 + hsB, voffB); PG8_STAGE(PG8_SA(0, 0), a2, voffA);
;             PG8_WAIT_V(8); PG8_WAIT_L(0); PG8_BAR; PG8_MMA(1, 0, At, B0); PG8_MMA(1, 1, At, B1); PG8_BAR; PG8_SCHED;
.LBB0_2884:
	ds_read_b128 v[118:121], v1
	ds_read_b128 v[148:151], v1 offset:1024
	ds_read_b128 v[152:155], v1 offset:2048
	ds_read_b128 v[156:159], v1 offset:3072
	ds_read_b128 v[160:163], v114
	ds_read_b128 v[164:167], v114 offset:1024
	ds_read_b128 v[168:171], v114 offset:2048
	ds_read_b128 v[172:175], v114 offset:3072
	s_add_u32 s14, s12, 0x100
	s_addc_u32 s15, s13, 0
	s_cmp_lg_u32 s33, 8
	s_cselect_b32 s16, s14, 0
	s_cselect_b32 s17, s15, 0
	s_add_u32 s18, s2, s16
	s_addc_u32 s19, s3, s17
	s_add_u32 s16, s0, s16
	s_addc_u32 s17, s1, s17
	s_mov_b32 m0, s34
	v_lshl_add_u64 v[208:209], v[110:111], 0, s[12:13]
	ds_read_b128 v[176:179], v115
	ds_read_b128 v[180:183], v115 offset:1024
	ds_read_b128 v[184:187], v115 offset:2048
	ds_read_b128 v[188:191], v115 offset:3072
	ds_read_b128 v[192:195], v115 offset:4096
	ds_read_b128 v[196:199], v115 offset:5120
	ds_read_b128 v[200:203], v115 offset:6144
	ds_read_b128 v[204:207], v115 offset:7168
	global_load_lds_dwordx4 v[208:209], off
	v_lshl_add_u64 v[208:209], v[112:113], 0, s[12:13]
	s_mov_b32 m0, s35
	s_nop 0
	global_load_lds_dwordx4 v[208:209], off
	s_waitcnt vmcnt(8)
	s_waitcnt lgkmcnt(0)
	s_setprio 1
	s_barrier
	s_waitcnt lgkmcnt(0)
	v_mfma_i32_16x16x64_i8 v[142:145], v[118:121], v[176:179], v[142:145]
	v_mfma_i32_16x16x64_i8 v[138:141], v[152:155], v[176:179], v[138:141]
	v_mfma_i32_16x16x64_i8 v[126:129], v[118:121], v[184:187], v[126:129]
	v_mfma_i32_16x16x64_i8 v[122:125], v[152:155], v[184:187], v[122:125]
	v_mfma_i32_16x16x64_i8 v[94:97], v[118:121], v[192:195], v[94:97]
	v_mfma_i32_16x16x64_i8 v[90:93], v[152:155], v[192:195], v[90:93]
	v_mfma_i32_16x16x64_i8 v[78:81], v[118:121], v[200:203], v[78:81]
	v_mfma_i32_16x16x64_i8 v[74:77], v[152:155], v[200:203], v[74:77]
	v_mfma_i32_16x16x64_i8 v[142:145], v[148:151], v[180:183], v[142:145]
	v_mfma_i32_16x16x64_i8 v[138:141], v[156:159], v[180:183], v[138:141]
	v_mfma_i32_16x16x64_i8 v[126:129], v[148:151], v[188:191], v[126:129]
	v_mfma_i32_16x16x64_i8 v[122:125], v[156:159], v[188:191], v[122:125]
	v_mfma_i32_16x16x64_i8 v[94:97], v[148:151], v[196:199], v[94:97]
	v_mfma_i32_16x16x64_i8 v[90:93], v[156:159], v[196:199], v[90:93]
	v_mfma_i32_16x16x64_i8 v[78:81], v[148:151], v[204:207], v[78:81]
	v_mfma_i32_16x16x64_i8 v[74:77], v[156:159], v[204:207], v[74:77]
	v_mfma_i32_16x16x64_i8 v[134:137], v[160:163], v[176:179], v[134:137]
	v_mfma_i32_16x16x64_i8 v[130:133], v[168:171], v[176:179], v[130:133]
	v_mfma_i32_16x16x64_i8 v[102:105], v[160:163], v[184:187], v[102:105]
	v_mfma_i32_16x16x64_i8 v[98:101], v[168:171], v[184:187], v[98:101]
	v_mfma_i32_16x16x64_i8 v[86:89], v[160:163], v[192:195], v[86:89]
	v_mfma_i32_16x16x64_i8 v[82:85], v[168:171], v[192:195], v[82:85]
	v_mfma_i32_16x16x64_i8 v[70:73], v[160:163], v[200:203], v[70:73]
	v_mfma_i32_16x16x64_i8 v[66:69], v[168:171], v[200:203], v[66:69]
	v_mfma_i32_16x16x64_i8 v[134:137], v[164:167], v[180:183], v[134:137]
	v_mfma_i32_16x16x64_i8 v[130:133], v[172:175], v[180:183], v[130:133]
	v_mfma_i32_16x16x64_i8 v[102:105], v[164:167], v[188:191], v[102:105]
	v_mfma_i32_16x16x64_i8 v[98:101], v[172:175], v[188:191], v[98:101]
	v_mfma_i32_16x16x64_i8 v[86:89], v[164:167], v[196:199], v[86:89]
	v_mfma_i32_16x16x64_i8 v[82:85], v[172:175], v[196:199], v[82:85]
	v_mfma_i32_16x16x64_i8 v[70:73], v[164:167], v[204:207], v[70:73]
	v_mfma_i32_16x16x64_i8 v[66:69], v[172:175], v[204:207], v[66:69]
	s_barrier
	s_setprio 0
	s_mov_b32 m0, s36
	v_lshl_add_u64 v[208:209], s[16:17], 0, v[108:109]
	s_add_u32 s12, s16, 0x180000
	ds_read_b128 v[176:179], v115 offset:16384
	ds_read_b128 v[180:183], v115 offset:17408
	ds_read_b128 v[184:187], v115 offset:18432
	ds_read_b128 v[188:191], v115 offset:19456
	ds_read_b128 v[192:195], v115 offset:20480
	ds_read_b128 v[196:199], v115 offset:21504
	ds_read_b128 v[200:203], v115 offset:22528
	ds_read_b128 v[204:207], v115 offset:23552
	global_load_lds_dwordx4 v[208:209], off
	v_lshl_add_u64 v[210:211], s[16:17], 0, v[106:107]
	s_mov_b32 m0, s37
	s_addc_u32 s13, s17, 0
	global_load_lds_dwordx4 v[210:211], off
	v_lshl_add_u64 v[212:213], s[12:13], 0, v[108:109]
	s_mov_b32 m0, s38
	v_lshl_add_u64 v[214:215], s[18:19], 0, v[106:107]
	global_load_lds_dwordx4 v[212:213], off
	v_lshl_add_u64 v[212:213], s[12:13], 0, v[106:107]
	s_mov_b32 m0, s39
	s_nop 0
	global_load_lds_dwordx4 v[212:213], off
	v_lshl_add_u64 v[212:213], s[18:19], 0, v[108:109]
	s_mov_b32 m0, s26
	s_nop 0
	global_load_lds_dwordx4 v[212:213], off
	s_mov_b32 m0, s27
	s_nop 0
	global_load_lds_dwordx4 v[214:215], off
	s_waitcnt vmcnt(8)
	s_waitcnt lgkmcnt(0)
	s_setprio 1
	s_barrier
; #define PG8_STAGE(bufoff, gbase, voff) do { _Pragma("unroll") for (int _i = 0; _i < 2; ++_i) \
;         __builtin_amdgcn_global_load_lds((const unsigned*)((const char*)(gbase) + (voff)[_i]), (LAS unsigned*)(lds + (bufoff) + ldsw + _i * 8192), 16, 0, 0); } while (0)
; #define PG8_LDA(dst, b, h) do { _Pragma("unroll") for (int m = 0; m < 4; ++m) _Pragma("unroll") for (int k = 0; k < 2; ++k) dst[m][k] = *(const LAS bf16x8*)(lds + PG8_SA(b, h) + aoff + m * 2048 + k * 1024); } while (0)
; #define PG8_LDB(dst, b, h) do { _Pragma("unroll") for (int n = 0; n < 2; ++n) _Pragma("unroll") for (int k = 0; k < 2; ++k) dst[n][k] = *(const LAS bf16x8*)(lds + PG8_SB(b, h) + boff + n * 2048 + k * 1024); } while (0)
; #define PG8_WAIT_V(n) asm volatile("s_waitcnt vmcnt(" #n ")" ::: "memory")
; #define PG8_WAIT_L(n) asm volatile("s_waitcnt lgkmcnt(" #n ")" ::: "memory")
; #define PG8_BAR __builtin_amdgcn_s_barrier()
; #define PG8_SCHED __builtin_amdgcn_sched_barrier(0)
; template <class Epi, class Geom, class Sched, bool ALIGN_EPI, bool I8 = false>
; __device__ __forceinline__ void gemm_phase(LAS unsigned char* lds, const Gemm g, const Sched& S, const Epi& E) {
;     ...
;             PG8_WAIT_V(8); PG8_WAIT_L(0); PG8_BAR; PG8_MMA(1, 0, At, B0); PG8_MMA(1, 1, At, B1); PG8_BAR; PG8_SCHED;
;             PG8_LDB(B0, 1, 0); PG8_LDB(B1, 1, 1); PG8_SCHED; PG8_LDA(At, 1, 0); PG8_STAGE(PG8_SA(0, 1), a2 + hsA, voffA);
;             PG8_WAIT_V(8); PG8_WAIT_L(0); PG8_BAR; PG8_MMA(0, 0, At, B0); PG8_MMA(0, 1, At, B1); PG8_BAR; PG8_SCHED;
	s_waitcnt lgkmcnt(0)
	v_mfma_i32_16x16x64_i8 v[62:65], v[118:121], v[176:179], v[62:65]
	v_mfma_i32_16x16x64_i8 v[58:61], v[152:155], v[176:179], v[58:61]
	v_mfma_i32_16x16x64_i8 v[46:49], v[118:121], v[184:187], v[46:49]
	v_mfma_i32_16x16x64_i8 v[42:45], v[152:155], v[184:187], v[42:45]
	v_mfma_i32_16x16x64_i8 v[30:33], v[118:121], v[192:195], v[30:33]
	v_mfma_i32_16x16x64_i8 v[26:29], v[152:155], v[192:195], v[26:29]
	v_mfma_i32_16x16x64_i8 v[14:17], v[118:121], v[200:203], v[14:17]
	v_mfma_i32_16x16x64_i8 v[10:13], v[152:155], v[200:203], v[10:13]
	v_mfma_i32_16x16x64_i8 v[62:65], v[148:151], v[180:183], v[62:65]
	v_mfma_i32_16x16x64_i8 v[58:61], v[156:159], v[180:183], v[58:61]
	v_mfma_i32_16x16x64_i8 v[46:49], v[148:151], v[188:191], v[46:49]
	v_mfma_i32_16x16x64_i8 v[42:45], v[156:159], v[188:191], v[42:45]
	v_mfma_i32_16x16x64_i8 v[30:33], v[148:151], v[196:199], v[30:33]
	v_mfma_i32_16x16x64_i8 v[26:29], v[156:159], v[196:199], v[26:29]
	v_mfma_i32_16x16x64_i8 v[14:17], v[148:151], v[204:207], v[14:17]
	v_mfma_i32_16x16x64_i8 v[10:13], v[156:159], v[204:207], v[10:13]
	v_mfma_i32_16x16x64_i8 v[54:57], v[160:163], v[176:179], v[54:57]
	v_mfma_i32_16x16x64_i8 v[50:53], v[168:171], v[176:179], v[50:53]
	v_mfma_i32_16x16x64_i8 v[38:41], v[160:163], v[184:187], v[38:41]
	v_mfma_i32_16x16x64_i8 v[34:37], v[168:171], v[184:187], v[34:37]
	v_mfma_i32_16x16x64_i8 v[22:25], v[160:163], v[192:195], v[22:25]
	v_mfma_i32_16x16x64_i8 v[18:21], v[168:171], v[192:195], v[18:21]
	v_mfma_i32_16x16x64_i8 v[6:9], v[160:163], v[200:203], v[6:9]
	v_mfma_i32_16x16x64_i8 v[2:5], v[168:171], v[200:203], v[2:5]
	v_mfma_i32_16x16x64_i8 v[54:57], v[164:167], v[180:183], v[54:57]
	v_mfma_i32_16x16x64_i8 v[50:53], v[172:175], v[180:183], v[50:53]
	v_mfma_i32_16x16x64_i8 v[38:41], v[164:167], v[188:191], v[38:41]
	v_mfma_i32_16x16x64_i8 v[34:37], v[172:175], v[188:191], v[34:37]
	v_mfma_i32_16x16x64_i8 v[22:25], v[164:167], v[196:199], v[22:25]
	v_mfma_i32_16x16x64_i8 v[18:21], v[172:175], v[196:199], v[18:21]
	v_mfma_i32_16x16x64_i8 v[6:9], v[164:167], v[204:207], v[6:9]
	v_mfma_i32_16x16x64_i8 v[2:5], v[172:175], v[204:207], v[2:5]
	s_barrier
	s_setprio 0
	ds_read_b128 v[118:121], v116
	ds_read_b128 v[148:151], v116 offset:1024
	ds_read_b128 v[152:155], v116 offset:2048
	ds_read_b128 v[156:159], v116 offset:3072
	ds_read_b128 v[160:163], v117
	ds_read_b128 v[164:167], v117 offset:1024
	ds_read_b128 v[168:171], v117 offset:2048
	ds_read_b128 v[172:175], v117 offset:3072
	s_add_u32 s12, s18, 0x180000
	s_addc_u32 s13, s19, 0
	s_mov_b32 m0, s28
	v_lshl_add_u64 v[216:217], s[12:13], 0, v[108:109]
	ds_read_b128 v[176:179], v115 offset:32768
	ds_read_b128 v[180:183], v115 offset:33792
	ds_read_b128 v[184:187], v115 offset:34816
	ds_read_b128 v[188:191], v115 offset:35840
	ds_read_b128 v[192:195], v115 offset:36864
	ds_read_b128 v[196:199], v115 offset:37888
	ds_read_b128 v[200:203], v115 offset:38912
	ds_read_b128 v[204:207], v115 offset:39936
	global_load_lds_dwordx4 v[216:217], off
	v_lshl_add_u64 v[216:217], s[12:13], 0, v[106:107]
	s_mov_b32 m0, s29
	s_nop 0
	global_load_lds_dwordx4 v[216:217], off
	s_waitcnt vmcnt(8)
	s_waitcnt lgkmcnt(0)
	s_setprio 1
	s_barrier
	s_waitcnt lgkmcnt(0)
	v_mfma_i32_16x16x64_i8 v[142:145], v[118:121], v[176:179], v[142:145]
	v_mfma_i32_16x16x64_i8 v[138:141], v[152:155], v[176:179], v[138:141]
	v_mfma_i32_16x16x64_i8 v[126:129], v[118:121], v[184:187], v[126:129]
	v_mfma_i32_16x16x64_i8 v[122:125], v[152:155], v[184:187], v[122:125]
	v_mfma_i32_16x16x64_i8 v[94:97], v[118:121], v[192:195], v[94:97]
	v_mfma_i32_16x16x64_i8 v[90:93], v[152:155], v[192:195], v[90:93]
	v_mfma_i32_16x16x64_i8 v[78:81], v[118:121], v[200:203], v[78:81]
	v_mfma_i32_16x16x64_i8 v[74:77], v[152:155], v[200:203], v[74:77]
	v_mfma_i32_16x16x64_i8 v[142:145], v[148:151], v[180:183], v[142:145]
	v_mfma_i32_16x16x64_i8 v[138:141], v[156:159], v[180:183], v[138:141]
	v_mfma_i32_16x16x64_i8 v[126:129], v[148:151], v[188:191], v[126:129]
	v_mfma_i32_16x16x64_i8 v[122:125], v[156:159], v[188:191], v[122:125]
	v_mfma_i32_16x16x64_i8 v[94:97], v[148:151], v[196:199], v[94:97]
	v_mfma_i32_16x16x64_i8 v[90:93], v[156:159], v[196:199], v[90:93]
	v_mfma_i32_16x16x64_i8 v[78:81], v[148:151], v[204:207], v[78:81]
	v_mfma_i32_16x16x64_i8 v[74:77], v[156:159], v[204:207], v[74:77]
	v_mfma_i32_16x16x64_i8 v[134:137], v[160:163], v[176:179], v[134:137]
	v_mfma_i32_16x16x64_i8 v[130:133], v[168:171], v[176:179], v[130:133]
	v_mfma_i32_16x16x64_i8 v[102:105], v[160:163], v[184:187], v[102:105]
	v_mfma_i32_16x16x64_i8 v[98:101], v[168:171], v[184:187], v[98:101]
	v_mfma_i32_16x16x64_i8 v[86:89], v[160:163], v[192:195], v[86:89]
	v_mfma_i32_16x16x64_i8 v[82:85], v[168:171], v[192:195], v[82:85]
	v_mfma_i32_16x16x64_i8 v[70:73], v[160:163], v[200:203], v[70:73]
	v_mfma_i32_16x16x64_i8 v[66:69], v[168:171], v[200:203], v[66:69]
	v_mfma_i32_16x16x64_i8 v[134:137], v[164:167], v[180:183], v[134:137]
	v_mfma_i32_16x16x64_i8 v[130:133], v[172:175], v[180:183], v[130:133]
	v_mfma_i32_16x16x64_i8 v[102:105], v[164:167], v[188:191], v[102:105]
	v_mfma_i32_16x16x64_i8 v[98:101], v[172:175], v[188:191], v[98:101]
	v_mfma_i32_16x16x64_i8 v[86:89], v[164:167], v[196:199], v[86:89]
	v_mfma_i32_16x16x64_i8 v[82:85], v[172:175], v[196:199], v[82:85]
	v_mfma_i32_16x16x64_i8 v[70:73], v[164:167], v[204:207], v[70:73]
	v_mfma_i32_16x16x64_i8 v[66:69], v[172:175], v[204:207], v[66:69]
	s_barrier
; #define PG8_STAGE(bufoff, gbase, voff) do { _Pragma("unroll") for (int _i = 0; _i < 2; ++_i) \
;         __builtin_amdgcn_global_load_lds((const unsigned*)((const char*)(gbase) + (voff)[_i]), (LAS unsigned*)(lds + (bufoff) + ldsw + _i * 8192), 16, 0, 0); } while (0)
; #define PG8_LDA(dst, b, h) do { _Pragma("unroll") for (int m = 0; m < 4; ++m) _Pragma("unroll") for (int k = 0; k < 2; ++k) dst[m][k] = *(const LAS bf16x8*)(lds + PG8_SA(b, h) + aoff + m * 2048 + k * 1024); } while (0)
; #define PG8_WAIT_V(n) asm volatile("s_waitcnt vmcnt(" #n ")" ::: "memory")
; #define PG8_WAIT_L(n) asm volatile("s_waitcnt lgkmcnt(" #n ")" ::: "memory")
; #define PG8_BAR __builtin_amdgcn_s_barrier()
; #define PG8_SCHED __builtin_amdgcn_sched_barrier(0)
; template <class Epi, class Geom, class Sched, bool ALIGN_EPI, bool I8 = false>
; __device__ __forceinline__ void gemm_phase(LAS unsigned char* lds, const Gemm g, const Sched& S, const Epi& E) {
;     ...
;             PG8_LDA(At, 1, 1); PG8_STAGE(PG8_SB(1, 0), b3, voffB); PG8_STAGE(PG8_SB(1, 1), b3 + hsB, voffB); PG8_STAGE(PG8_SA(1, 0), a3, voffA);
;             PG8_WAIT_V(8); PG8_WAIT_L(0); PG8_BAR; PG8_MMA(1, 0, At, B0); PG8_MMA(1, 1, At, B1); PG8_BAR; PG8_SCHED;
;         }
	s_setprio 0
	s_mov_b32 m0, s40
	v_lshl_add_u64 v[208:209], v[208:209], 0, s[4:5]
	s_add_u32 s12, s16, 0x180080
	ds_read_b128 v[176:179], v115 offset:49152
	ds_read_b128 v[180:183], v115 offset:50176
	ds_read_b128 v[184:187], v115 offset:51200
	ds_read_b128 v[188:191], v115 offset:52224
	ds_read_b128 v[192:195], v115 offset:53248
	ds_read_b128 v[196:199], v115 offset:54272
	ds_read_b128 v[200:203], v115 offset:55296
	ds_read_b128 v[204:207], v115 offset:56320
	global_load_lds_dwordx4 v[208:209], off
	v_lshl_add_u64 v[208:209], v[210:211], 0, s[4:5]
	s_mov_b32 m0, s41
	s_addc_u32 s13, s17, 0
	global_load_lds_dwordx4 v[208:209], off
	v_lshl_add_u64 v[208:209], s[12:13], 0, v[108:109]
	s_mov_b32 m0, s42
	s_nop 0
	global_load_lds_dwordx4 v[208:209], off
	v_lshl_add_u64 v[208:209], s[12:13], 0, v[106:107]
	s_mov_b32 m0, s43
	s_nop 0
	global_load_lds_dwordx4 v[208:209], off
	v_lshl_add_u64 v[208:209], v[212:213], 0, s[4:5]
	s_mov_b32 m0, s30
	s_nop 0
	global_load_lds_dwordx4 v[208:209], off
	v_lshl_add_u64 v[208:209], v[214:215], 0, s[4:5]
	s_mov_b32 m0, s31
	s_nop 0
	global_load_lds_dwordx4 v[208:209], off
	s_waitcnt vmcnt(8)
	s_waitcnt lgkmcnt(0)
	s_setprio 1
	s_barrier
	s_waitcnt lgkmcnt(0)
	v_mfma_i32_16x16x64_i8 v[62:65], v[118:121], v[176:179], v[62:65]
	v_mfma_i32_16x16x64_i8 v[58:61], v[152:155], v[176:179], v[58:61]
	v_mfma_i32_16x16x64_i8 v[46:49], v[118:121], v[184:187], v[46:49]
	v_mfma_i32_16x16x64_i8 v[42:45], v[152:155], v[184:187], v[42:45]
	v_mfma_i32_16x16x64_i8 v[30:33], v[118:121], v[192:195], v[30:33]
	v_mfma_i32_16x16x64_i8 v[26:29], v[152:155], v[192:195], v[26:29]
	v_mfma_i32_16x16x64_i8 v[14:17], v[118:121], v[200:203], v[14:17]
	v_mfma_i32_16x16x64_i8 v[10:13], v[152:155], v[200:203], v[10:13]
	v_mfma_i32_16x16x64_i8 v[62:65], v[148:151], v[180:183], v[62:65]
	v_mfma_i32_16x16x64_i8 v[58:61], v[156:159], v[180:183], v[58:61]
	v_mfma_i32_16x16x64_i8 v[46:49], v[148:151], v[188:191], v[46:49]
	v_mfma_i32_16x16x64_i8 v[42:45], v[156:159], v[188:191], v[42:45]
	v_mfma_i32_16x16x64_i8 v[30:33], v[148:151], v[196:199], v[30:33]
	v_mfma_i32_16x16x64_i8 v[26:29], v[156:159], v[196:199], v[26:29]
	v_mfma_i32_16x16x64_i8 v[14:17], v[148:151], v[204:207], v[14:17]
	v_mfma_i32_16x16x64_i8 v[10:13], v[156:159], v[204:207], v[10:13]
	v_mfma_i32_16x16x64_i8 v[54:57], v[160:163], v[176:179], v[54:57]
	v_mfma_i32_16x16x64_i8 v[50:53], v[168:171], v[176:179], v[50:53]
	v_mfma_i32_16x16x64_i8 v[38:41], v[160:163], v[184:187], v[38:41]
	v_mfma_i32_16x16x64_i8 v[34:37], v[168:171], v[184:187], v[34:37]
	v_mfma_i32_16x16x64_i8 v[22:25], v[160:163], v[192:195], v[22:25]
	v_mfma_i32_16x16x64_i8 v[18:21], v[168:171], v[192:195], v[18:21]
	v_mfma_i32_16x16x64_i8 v[6:9], v[160:163], v[200:203], v[6:9]
	v_mfma_i32_16x16x64_i8 v[2:5], v[168:171], v[200:203], v[2:5]
	v_mfma_i32_16x16x64_i8 v[54:57], v[164:167], v[180:183], v[54:57]
	v_mfma_i32_16x16x64_i8 v[50:53], v[172:175], v[180:183], v[50:53]
	v_mfma_i32_16x16x64_i8 v[38:41], v[164:167], v[188:191], v[38:41]
	v_mfma_i32_16x16x64_i8 v[34:37], v[172:175], v[188:191], v[34:37]
	v_mfma_i32_16x16x64_i8 v[22:25], v[164:167], v[196:199], v[22:25]
	v_mfma_i32_16x16x64_i8 v[18:21], v[172:175], v[196:199], v[18:21]
	v_mfma_i32_16x16x64_i8 v[6:9], v[164:167], v[204:207], v[6:9]
	v_mfma_i32_16x16x64_i8 v[2:5], v[172:175], v[204:207], v[2:5]
	s_barrier
	s_setprio 0
	s_add_i32 s33, s33, 2
	s_cmp_gt_u32 s33, 9
	s_mov_b64 s[12:13], s[14:15]
	s_cbranch_scc0 .LBB0_2884
	s_cmpk_lt_u32 s23, 0x100
	s_cbranch_scc0 .LBB0_2887
	s_barrier
